# K-loops: drop the compiler's duplicate s_waitcnt lgkmcnt(0) after the template's own wait (36 sites)
# baseline (speedup 1.0000x reference)
.LBB0_57:
	s_add_u32 s22, s0, 0xfffc0080
	s_addc_u32 s23, s1, -1
	s_add_i32 s65, 0, 0x10000
	v_add_u32_e32 v142, s65, v178
	ds_read_b128 v[130:133], v142
	ds_read_b128 v[134:137], v142 offset:1024
	ds_read_b128 v[138:141], v142 offset:2048
	ds_read_b128 v[142:145], v142 offset:3072
	s_cmp_eq_u32 s64, 12
	s_cselect_b32 s49, s37, s23
	s_cselect_b32 s48, s60, s22
	s_cselect_b32 s23, s35, s63
	s_cselect_b32 s22, s61, s62
	v_lshl_add_u64 v[186:187], s[0:1], 0, v[168:169]
	s_add_i32 m0, s47, 0xc000
	ds_read_b128 v[172:175], v180
	ds_read_b128 v[182:185], v180 offset:1024
	ds_read_b128 v[206:209], v180 offset:2048
	ds_read_b128 v[210:213], v180 offset:3072
	ds_read_b128 v[214:217], v180 offset:4096
	ds_read_b128 v[218:221], v180 offset:5120
	ds_read_b128 v[222:225], v180 offset:6144
	ds_read_b128 v[226:229], v180 offset:7168
	global_load_lds_dwordx4 v[186:187], off
	v_lshl_add_u64 v[186:187], s[0:1], 0, v[170:171]
	s_add_i32 m0, s47, 0xe000
	s_nop 0
	global_load_lds_dwordx4 v[186:187], off
	s_waitcnt lgkmcnt(8)
	s_barrier
	s_waitcnt lgkmcnt(0)
	s_setprio 1
	v_mfma_f32_16x16x32_bf16 v[126:129], v[130:133], v[172:175], v[126:129]
	v_mfma_f32_16x16x32_bf16 v[122:125], v[138:141], v[172:175], v[122:125]
	v_mfma_f32_16x16x32_bf16 v[114:117], v[130:133], v[206:209], v[114:117]
	v_mfma_f32_16x16x32_bf16 v[106:109], v[138:141], v[206:209], v[106:109]
	v_mfma_f32_16x16x32_bf16 v[98:101], v[130:133], v[214:217], v[98:101]
	v_mfma_f32_16x16x32_bf16 v[90:93], v[138:141], v[214:217], v[90:93]
	v_mfma_f32_16x16x32_bf16 v[82:85], v[130:133], v[222:225], v[82:85]
	v_mfma_f32_16x16x32_bf16 v[74:77], v[138:141], v[222:225], v[74:77]
	v_mfma_f32_16x16x32_bf16 v[126:129], v[134:137], v[182:185], v[126:129]
	v_mfma_f32_16x16x32_bf16 v[122:125], v[142:145], v[182:185], v[122:125]
	v_mfma_f32_16x16x32_bf16 v[114:117], v[134:137], v[210:213], v[114:117]
	v_mfma_f32_16x16x32_bf16 v[106:109], v[142:145], v[210:213], v[106:109]
	v_mfma_f32_16x16x32_bf16 v[98:101], v[134:137], v[218:221], v[98:101]
	v_mfma_f32_16x16x32_bf16 v[90:93], v[142:145], v[218:221], v[90:93]
	v_mfma_f32_16x16x32_bf16 v[82:85], v[134:137], v[226:229], v[82:85]
	v_mfma_f32_16x16x32_bf16 v[74:77], v[142:145], v[226:229], v[74:77]
	s_setprio 0
	s_barrier
	s_add_i32 s68, 0, 0x14000
	s_add_i32 s65, s65, s27
	v_add_u32_e32 v181, s68, v178
	v_lshl_add_u64 v[186:187], s[22:23], 0, v[0:1]
	s_mov_b32 m0, s65
	ds_read_b128 v[230:233], v181
	ds_read_b128 v[234:237], v181 offset:1024
	ds_read_b128 v[238:241], v181 offset:2048
	ds_read_b128 v[242:245], v181 offset:3072
	global_load_lds_dwordx4 v[186:187], off
	v_lshl_add_u64 v[246:247], s[22:23], 0, v[166:167]
	s_add_i32 m0, s65, 0x2000
	s_nop 0
	global_load_lds_dwordx4 v[246:247], off
	s_barrier
	s_waitcnt lgkmcnt(0)
	s_setprio 1
	v_mfma_f32_16x16x32_bf16 v[118:121], v[230:233], v[172:175], v[118:121]
	v_mfma_f32_16x16x32_bf16 v[110:113], v[238:241], v[172:175], v[110:113]
	v_mfma_f32_16x16x32_bf16 v[102:105], v[230:233], v[206:209], v[102:105]
	v_mfma_f32_16x16x32_bf16 v[94:97], v[238:241], v[206:209], v[94:97]
	v_mfma_f32_16x16x32_bf16 v[86:89], v[230:233], v[214:217], v[86:89]
	v_mfma_f32_16x16x32_bf16 v[78:81], v[238:241], v[214:217], v[78:81]
	v_mfma_f32_16x16x32_bf16 v[70:73], v[230:233], v[222:225], v[70:73]
	v_mfma_f32_16x16x32_bf16 v[66:69], v[238:241], v[222:225], v[66:69]
	v_mfma_f32_16x16x32_bf16 v[118:121], v[234:237], v[182:185], v[118:121]
	v_mfma_f32_16x16x32_bf16 v[110:113], v[242:245], v[182:185], v[110:113]
	v_mfma_f32_16x16x32_bf16 v[102:105], v[234:237], v[210:213], v[102:105]
	v_mfma_f32_16x16x32_bf16 v[94:97], v[242:245], v[210:213], v[94:97]
	v_mfma_f32_16x16x32_bf16 v[86:89], v[234:237], v[218:221], v[86:89]
	v_mfma_f32_16x16x32_bf16 v[78:81], v[242:245], v[218:221], v[78:81]
	v_mfma_f32_16x16x32_bf16 v[70:73], v[234:237], v[226:229], v[70:73]
	v_mfma_f32_16x16x32_bf16 v[66:69], v[242:245], v[226:229], v[66:69]
	s_setprio 0
	s_mov_b32 m0, s47
	v_lshl_add_u64 v[248:249], s[48:49], 0, v[162:163]
	s_barrier
	ds_read_b128 v[172:175], v180 offset:16384
	ds_read_b128 v[182:185], v180 offset:17408
	ds_read_b128 v[206:209], v180 offset:18432
	ds_read_b128 v[210:213], v180 offset:19456
	ds_read_b128 v[214:217], v180 offset:20480
	ds_read_b128 v[218:221], v180 offset:21504
	ds_read_b128 v[222:225], v180 offset:22528
	ds_read_b128 v[226:229], v180 offset:23552
	global_load_lds_dwordx4 v[248:249], off
	v_lshl_add_u64 v[250:251], s[48:49], 0, v[164:165]
	s_mov_b32 m0, s50
	s_nop 0
	global_load_lds_dwordx4 v[250:251], off
	s_barrier
	s_waitcnt lgkmcnt(0)
	s_setprio 1
	v_mfma_f32_16x16x32_bf16 v[62:65], v[130:133], v[172:175], v[62:65]
	v_mfma_f32_16x16x32_bf16 v[58:61], v[138:141], v[172:175], v[58:61]
	v_mfma_f32_16x16x32_bf16 v[50:53], v[130:133], v[206:209], v[50:53]
	v_mfma_f32_16x16x32_bf16 v[42:45], v[138:141], v[206:209], v[42:45]
	v_mfma_f32_16x16x32_bf16 v[34:37], v[130:133], v[214:217], v[34:37]
	v_mfma_f32_16x16x32_bf16 v[26:29], v[138:141], v[214:217], v[26:29]
	v_mfma_f32_16x16x32_bf16 v[18:21], v[130:133], v[222:225], v[18:21]
	v_mfma_f32_16x16x32_bf16 v[10:13], v[138:141], v[222:225], v[10:13]
	v_mfma_f32_16x16x32_bf16 v[62:65], v[134:137], v[182:185], v[62:65]
	v_mfma_f32_16x16x32_bf16 v[58:61], v[142:145], v[182:185], v[58:61]
	v_mfma_f32_16x16x32_bf16 v[50:53], v[134:137], v[210:213], v[50:53]
	v_mfma_f32_16x16x32_bf16 v[42:45], v[142:145], v[210:213], v[42:45]
	v_mfma_f32_16x16x32_bf16 v[34:37], v[134:137], v[218:221], v[34:37]
	v_mfma_f32_16x16x32_bf16 v[26:29], v[142:145], v[218:221], v[26:29]
	v_mfma_f32_16x16x32_bf16 v[18:21], v[134:137], v[226:229], v[18:21]
	v_mfma_f32_16x16x32_bf16 v[10:13], v[142:145], v[226:229], v[10:13]
	s_setprio 0
	s_barrier
	s_add_u32 s66, s22, 0x40000
	s_addc_u32 s67, s23, 0
	s_add_i32 s65, s68, s27
	v_lshl_add_u64 v[130:131], s[66:67], 0, v[0:1]
	s_mov_b32 m0, s65
	s_nop 0
	global_load_lds_dwordx4 v[130:131], off
	v_lshl_add_u64 v[130:131], s[66:67], 0, v[166:167]
	s_add_i32 m0, s65, 0x2000
	s_nop 0
	global_load_lds_dwordx4 v[130:131], off
	s_waitcnt vmcnt(6)
	s_barrier
	s_setprio 1
	v_mfma_f32_16x16x32_bf16 v[54:57], v[230:233], v[172:175], v[54:57]
	v_mfma_f32_16x16x32_bf16 v[46:49], v[238:241], v[172:175], v[46:49]
	v_mfma_f32_16x16x32_bf16 v[38:41], v[230:233], v[206:209], v[38:41]
	v_mfma_f32_16x16x32_bf16 v[30:33], v[238:241], v[206:209], v[30:33]
	v_mfma_f32_16x16x32_bf16 v[22:25], v[230:233], v[214:217], v[22:25]
	v_mfma_f32_16x16x32_bf16 v[14:17], v[238:241], v[214:217], v[14:17]
	v_mfma_f32_16x16x32_bf16 v[6:9], v[230:233], v[222:225], v[6:9]
	v_mfma_f32_16x16x32_bf16 v[2:5], v[238:241], v[222:225], v[2:5]
	v_mfma_f32_16x16x32_bf16 v[54:57], v[234:237], v[182:185], v[54:57]
	v_mfma_f32_16x16x32_bf16 v[46:49], v[242:245], v[182:185], v[46:49]
	v_mfma_f32_16x16x32_bf16 v[38:41], v[234:237], v[210:213], v[38:41]
	v_mfma_f32_16x16x32_bf16 v[30:33], v[242:245], v[210:213], v[30:33]
	v_mfma_f32_16x16x32_bf16 v[22:25], v[234:237], v[218:221], v[22:25]
	v_mfma_f32_16x16x32_bf16 v[14:17], v[242:245], v[218:221], v[14:17]
	v_mfma_f32_16x16x32_bf16 v[6:9], v[234:237], v[226:229], v[6:9]
	v_mfma_f32_16x16x32_bf16 v[2:5], v[242:245], v[226:229], v[2:5]
	s_setprio 0
	s_add_i32 s65, 0, 0x18000
	v_add_u32_e32 v142, s65, v178
	s_barrier
	ds_read_b128 v[130:133], v142
	ds_read_b128 v[134:137], v142 offset:1024
	ds_read_b128 v[138:141], v142 offset:2048
	ds_read_b128 v[142:145], v142 offset:3072
	s_add_u32 s48, s48, 0x40000
	s_addc_u32 s49, s49, 0
	s_mov_b32 m0, s51
	v_lshl_add_u64 v[230:231], s[48:49], 0, v[162:163]
	ds_read_b128 v[172:175], v180 offset:32768
	ds_read_b128 v[182:185], v180 offset:33792
	ds_read_b128 v[206:209], v180 offset:34816
	ds_read_b128 v[210:213], v180 offset:35840
	ds_read_b128 v[214:217], v180 offset:36864
	ds_read_b128 v[218:221], v180 offset:37888
	ds_read_b128 v[222:225], v180 offset:38912
	ds_read_b128 v[226:229], v180 offset:39936
	global_load_lds_dwordx4 v[230:231], off
	v_lshl_add_u64 v[230:231], s[48:49], 0, v[164:165]
	s_mov_b32 m0, s54
	s_nop 0
	global_load_lds_dwordx4 v[230:231], off
	s_waitcnt lgkmcnt(8)
	s_barrier
	s_waitcnt lgkmcnt(0)
	s_setprio 1
	v_mfma_f32_16x16x32_bf16 v[126:129], v[130:133], v[172:175], v[126:129]
	v_mfma_f32_16x16x32_bf16 v[122:125], v[138:141], v[172:175], v[122:125]
	v_mfma_f32_16x16x32_bf16 v[114:117], v[130:133], v[206:209], v[114:117]
	v_mfma_f32_16x16x32_bf16 v[106:109], v[138:141], v[206:209], v[106:109]
	v_mfma_f32_16x16x32_bf16 v[98:101], v[130:133], v[214:217], v[98:101]
	v_mfma_f32_16x16x32_bf16 v[90:93], v[138:141], v[214:217], v[90:93]
	v_mfma_f32_16x16x32_bf16 v[82:85], v[130:133], v[222:225], v[82:85]
	v_mfma_f32_16x16x32_bf16 v[74:77], v[138:141], v[222:225], v[74:77]
	v_mfma_f32_16x16x32_bf16 v[126:129], v[134:137], v[182:185], v[126:129]
	v_mfma_f32_16x16x32_bf16 v[122:125], v[142:145], v[182:185], v[122:125]
	v_mfma_f32_16x16x32_bf16 v[114:117], v[134:137], v[210:213], v[114:117]
	v_mfma_f32_16x16x32_bf16 v[106:109], v[142:145], v[210:213], v[106:109]
	v_mfma_f32_16x16x32_bf16 v[98:101], v[134:137], v[218:221], v[98:101]
	v_mfma_f32_16x16x32_bf16 v[90:93], v[142:145], v[218:221], v[90:93]
	v_mfma_f32_16x16x32_bf16 v[82:85], v[134:137], v[226:229], v[82:85]
	v_mfma_f32_16x16x32_bf16 v[74:77], v[142:145], v[226:229], v[74:77]
	s_setprio 0
	s_barrier
	s_add_i32 s48, 0, 0x1c000
	s_add_i32 s49, s65, s27
	v_add_u32_e32 v181, s48, v178
	v_lshl_add_u64 v[186:187], v[186:187], 0, s[94:95]
	s_mov_b32 m0, s49
	ds_read_b128 v[230:233], v181
	ds_read_b128 v[234:237], v181 offset:1024
	ds_read_b128 v[238:241], v181 offset:2048
	ds_read_b128 v[242:245], v181 offset:3072
	global_load_lds_dwordx4 v[186:187], off
	v_lshl_add_u64 v[186:187], v[246:247], 0, s[94:95]
	s_add_i32 m0, s49, 0x2000
	s_nop 0
	global_load_lds_dwordx4 v[186:187], off
	s_barrier
	s_waitcnt lgkmcnt(0)
	s_setprio 1
	v_mfma_f32_16x16x32_bf16 v[118:121], v[230:233], v[172:175], v[118:121]
	v_mfma_f32_16x16x32_bf16 v[110:113], v[238:241], v[172:175], v[110:113]
	v_mfma_f32_16x16x32_bf16 v[102:105], v[230:233], v[206:209], v[102:105]
	v_mfma_f32_16x16x32_bf16 v[94:97], v[238:241], v[206:209], v[94:97]
	v_mfma_f32_16x16x32_bf16 v[86:89], v[230:233], v[214:217], v[86:89]
	v_mfma_f32_16x16x32_bf16 v[78:81], v[238:241], v[214:217], v[78:81]
	v_mfma_f32_16x16x32_bf16 v[70:73], v[230:233], v[222:225], v[70:73]
	v_mfma_f32_16x16x32_bf16 v[66:69], v[238:241], v[222:225], v[66:69]
	v_mfma_f32_16x16x32_bf16 v[118:121], v[234:237], v[182:185], v[118:121]
	v_mfma_f32_16x16x32_bf16 v[110:113], v[242:245], v[182:185], v[110:113]
	v_mfma_f32_16x16x32_bf16 v[102:105], v[234:237], v[210:213], v[102:105]
	v_mfma_f32_16x16x32_bf16 v[94:97], v[242:245], v[210:213], v[94:97]
	v_mfma_f32_16x16x32_bf16 v[86:89], v[234:237], v[218:221], v[86:89]
	v_mfma_f32_16x16x32_bf16 v[78:81], v[242:245], v[218:221], v[78:81]
	v_mfma_f32_16x16x32_bf16 v[70:73], v[234:237], v[226:229], v[70:73]
	v_mfma_f32_16x16x32_bf16 v[66:69], v[242:245], v[226:229], v[66:69]
	s_setprio 0
	s_mov_b32 m0, s55
	v_lshl_add_u64 v[186:187], v[248:249], 0, s[94:95]
	s_barrier
	ds_read_b128 v[172:175], v180 offset:49152
	ds_read_b128 v[182:185], v180 offset:50176
	ds_read_b128 v[206:209], v180 offset:51200
	ds_read_b128 v[210:213], v180 offset:52224
	ds_read_b128 v[214:217], v180 offset:53248
	ds_read_b128 v[218:221], v180 offset:54272
	ds_read_b128 v[222:225], v180 offset:55296
	ds_read_b128 v[226:229], v180 offset:56320
	global_load_lds_dwordx4 v[186:187], off
	v_lshl_add_u64 v[186:187], v[250:251], 0, s[94:95]
	s_mov_b32 m0, s56
	s_nop 0
	global_load_lds_dwordx4 v[186:187], off
	s_barrier
	s_waitcnt lgkmcnt(0)
	s_setprio 1
	v_mfma_f32_16x16x32_bf16 v[62:65], v[130:133], v[172:175], v[62:65]
	v_mfma_f32_16x16x32_bf16 v[58:61], v[138:141], v[172:175], v[58:61]
	v_mfma_f32_16x16x32_bf16 v[50:53], v[130:133], v[206:209], v[50:53]
	v_mfma_f32_16x16x32_bf16 v[42:45], v[138:141], v[206:209], v[42:45]
	v_mfma_f32_16x16x32_bf16 v[34:37], v[130:133], v[214:217], v[34:37]
	v_mfma_f32_16x16x32_bf16 v[26:29], v[138:141], v[214:217], v[26:29]
	v_mfma_f32_16x16x32_bf16 v[18:21], v[130:133], v[222:225], v[18:21]
	v_mfma_f32_16x16x32_bf16 v[10:13], v[138:141], v[222:225], v[10:13]
	v_mfma_f32_16x16x32_bf16 v[62:65], v[134:137], v[182:185], v[62:65]
	v_mfma_f32_16x16x32_bf16 v[58:61], v[142:145], v[182:185], v[58:61]
	v_mfma_f32_16x16x32_bf16 v[50:53], v[134:137], v[210:213], v[50:53]
	v_mfma_f32_16x16x32_bf16 v[42:45], v[142:145], v[210:213], v[42:45]
	v_mfma_f32_16x16x32_bf16 v[34:37], v[134:137], v[218:221], v[34:37]
	v_mfma_f32_16x16x32_bf16 v[26:29], v[142:145], v[218:221], v[26:29]
	v_mfma_f32_16x16x32_bf16 v[18:21], v[134:137], v[226:229], v[18:21]
	v_mfma_f32_16x16x32_bf16 v[10:13], v[142:145], v[226:229], v[10:13]
	s_setprio 0
	s_barrier
	s_add_u32 s22, s22, 0x40080
	s_addc_u32 s23, s23, 0
	s_add_i32 s48, s48, s27
	v_lshl_add_u64 v[130:131], s[22:23], 0, v[0:1]
	s_mov_b32 m0, s48
	s_nop 0
	global_load_lds_dwordx4 v[130:131], off
	v_lshl_add_u64 v[130:131], s[22:23], 0, v[166:167]
	s_add_i32 m0, s48, 0x2000
	s_nop 0
	global_load_lds_dwordx4 v[130:131], off
	s_waitcnt vmcnt(6)
	s_barrier
	s_setprio 1
	v_mfma_f32_16x16x32_bf16 v[54:57], v[230:233], v[172:175], v[54:57]
	v_mfma_f32_16x16x32_bf16 v[46:49], v[238:241], v[172:175], v[46:49]
	v_mfma_f32_16x16x32_bf16 v[38:41], v[230:233], v[206:209], v[38:41]
	v_mfma_f32_16x16x32_bf16 v[30:33], v[238:241], v[206:209], v[30:33]
	v_mfma_f32_16x16x32_bf16 v[22:25], v[230:233], v[214:217], v[22:25]
	v_mfma_f32_16x16x32_bf16 v[14:17], v[238:241], v[214:217], v[14:17]
	v_mfma_f32_16x16x32_bf16 v[6:9], v[230:233], v[222:225], v[6:9]
	v_mfma_f32_16x16x32_bf16 v[2:5], v[238:241], v[222:225], v[2:5]
	v_mfma_f32_16x16x32_bf16 v[54:57], v[234:237], v[182:185], v[54:57]
	v_mfma_f32_16x16x32_bf16 v[46:49], v[242:245], v[182:185], v[46:49]
	v_mfma_f32_16x16x32_bf16 v[38:41], v[234:237], v[210:213], v[38:41]
	v_mfma_f32_16x16x32_bf16 v[30:33], v[242:245], v[210:213], v[30:33]
	v_mfma_f32_16x16x32_bf16 v[22:25], v[234:237], v[218:221], v[22:25]
	v_mfma_f32_16x16x32_bf16 v[14:17], v[242:245], v[218:221], v[14:17]
	v_mfma_f32_16x16x32_bf16 v[6:9], v[234:237], v[226:229], v[6:9]
	v_mfma_f32_16x16x32_bf16 v[2:5], v[242:245], v[226:229], v[2:5]
	s_setprio 0
	s_add_i32 s64, s64, 2
	s_add_u32 s0, s0, 0x100
	s_addc_u32 s1, s1, 0
	s_add_u32 s62, s62, 0x100
	s_addc_u32 s63, s63, 0
	s_cmp_gt_u32 s64, 13
	s_barrier
	s_cbranch_scc0 .LBB0_57
	v_lshl_or_b32 v172, s59, 8, v179
	v_ashrrev_i32_e32 v173, 31, v172
	v_cndmask_b32_e64 v131, 0, 1, s[2:3]
	v_lshl_add_u64 v[174:175], v[172:173], 2, s[8:9]
	v_mov_b32_e32 v130, 0
	v_cmp_ne_u32_e64 s[0:1], 1, v131
	s_andn2_b64 vcc, exec, s[2:3]
	v_mov_b32_e32 v134, 0
	v_mov_b32_e32 v135, 0
	v_mov_b32_e32 v136, 0
	v_mov_b32_e32 v137, 0
	s_cbranch_vccnz .LBB0_60
	global_load_dwordx4 v[134:137], v[174:175], off

.LBB0_95:
	s_add_u32 s22, s8, 0xfffc0080
	s_addc_u32 s23, s9, -1
	s_add_i32 s63, 0, 0x10000
	v_add_u32_e32 v78, s63, v178
	ds_read_b128 v[58:61], v78
	ds_read_b128 v[66:69], v78 offset:1024
	ds_read_b128 v[74:77], v78 offset:2048
	ds_read_b128 v[78:81], v78 offset:3072
	s_cmp_eq_u32 s49, 12
	s_cselect_b32 s29, s25, s23
	s_cselect_b32 s28, s26, s22
	s_cselect_b32 s23, s27, s47
	s_cselect_b32 s22, s30, s31
	v_lshl_add_u64 v[186:187], s[8:9], 0, v[168:169]
	s_add_i32 m0, s3, 0xc000
	ds_read_b128 v[172:175], v180
	ds_read_b128 v[182:185], v180 offset:1024
	ds_read_b128 v[206:209], v180 offset:2048
	ds_read_b128 v[210:213], v180 offset:3072
	ds_read_b128 v[214:217], v180 offset:4096
	ds_read_b128 v[218:221], v180 offset:5120
	ds_read_b128 v[222:225], v180 offset:6144
	ds_read_b128 v[226:229], v180 offset:7168
	global_load_lds_dwordx4 v[186:187], off
	v_lshl_add_u64 v[186:187], s[8:9], 0, v[170:171]
	s_add_i32 m0, s3, 0xe000
	s_nop 0
	global_load_lds_dwordx4 v[186:187], off
	s_waitcnt lgkmcnt(8)
	s_barrier
	s_waitcnt lgkmcnt(0)
	s_setprio 1
	v_mfma_f32_16x16x32_bf16 v[142:145], v[58:61], v[172:175], v[142:145]
	v_mfma_f32_16x16x32_bf16 v[138:141], v[74:77], v[172:175], v[138:141]
	v_mfma_f32_16x16x32_bf16 v[126:129], v[58:61], v[206:209], v[126:129]
	v_mfma_f32_16x16x32_bf16 v[118:121], v[74:77], v[206:209], v[118:121]
	v_mfma_f32_16x16x32_bf16 v[110:113], v[58:61], v[214:217], v[110:113]
	v_mfma_f32_16x16x32_bf16 v[102:105], v[74:77], v[214:217], v[102:105]
	v_mfma_f32_16x16x32_bf16 v[94:97], v[58:61], v[222:225], v[94:97]
	v_mfma_f32_16x16x32_bf16 v[86:89], v[74:77], v[222:225], v[86:89]
	v_mfma_f32_16x16x32_bf16 v[142:145], v[66:69], v[182:185], v[142:145]
	v_mfma_f32_16x16x32_bf16 v[138:141], v[78:81], v[182:185], v[138:141]
	v_mfma_f32_16x16x32_bf16 v[126:129], v[66:69], v[210:213], v[126:129]
	v_mfma_f32_16x16x32_bf16 v[118:121], v[78:81], v[210:213], v[118:121]
	v_mfma_f32_16x16x32_bf16 v[110:113], v[66:69], v[218:221], v[110:113]
	v_mfma_f32_16x16x32_bf16 v[102:105], v[78:81], v[218:221], v[102:105]
	v_mfma_f32_16x16x32_bf16 v[94:97], v[66:69], v[226:229], v[94:97]
	v_mfma_f32_16x16x32_bf16 v[86:89], v[78:81], v[226:229], v[86:89]
	s_setprio 0
	s_barrier
	s_add_i32 s66, 0, 0x14000
	s_add_i32 s63, s63, s37
	v_add_u32_e32 v181, s66, v178
	v_lshl_add_u64 v[186:187], s[22:23], 0, v[0:1]
	s_mov_b32 m0, s63
	ds_read_b128 v[230:233], v181
	ds_read_b128 v[234:237], v181 offset:1024
	ds_read_b128 v[238:241], v181 offset:2048
	ds_read_b128 v[242:245], v181 offset:3072
	global_load_lds_dwordx4 v[186:187], off
	v_lshl_add_u64 v[246:247], s[22:23], 0, v[166:167]
	s_add_i32 m0, s63, 0x2000
	s_nop 0
	global_load_lds_dwordx4 v[246:247], off
	s_barrier
	s_waitcnt lgkmcnt(0)
	s_setprio 1
	v_mfma_f32_16x16x32_bf16 v[134:137], v[230:233], v[172:175], v[134:137]
	v_mfma_f32_16x16x32_bf16 v[130:133], v[238:241], v[172:175], v[130:133]
	v_mfma_f32_16x16x32_bf16 v[122:125], v[230:233], v[206:209], v[122:125]
	v_mfma_f32_16x16x32_bf16 v[114:117], v[238:241], v[206:209], v[114:117]
	v_mfma_f32_16x16x32_bf16 v[106:109], v[230:233], v[214:217], v[106:109]
	v_mfma_f32_16x16x32_bf16 v[98:101], v[238:241], v[214:217], v[98:101]
	v_mfma_f32_16x16x32_bf16 v[90:93], v[230:233], v[222:225], v[90:93]
	v_mfma_f32_16x16x32_bf16 v[82:85], v[238:241], v[222:225], v[82:85]
	v_mfma_f32_16x16x32_bf16 v[134:137], v[234:237], v[182:185], v[134:137]
	v_mfma_f32_16x16x32_bf16 v[130:133], v[242:245], v[182:185], v[130:133]
	v_mfma_f32_16x16x32_bf16 v[122:125], v[234:237], v[210:213], v[122:125]
	v_mfma_f32_16x16x32_bf16 v[114:117], v[242:245], v[210:213], v[114:117]
	v_mfma_f32_16x16x32_bf16 v[106:109], v[234:237], v[218:221], v[106:109]
	v_mfma_f32_16x16x32_bf16 v[98:101], v[242:245], v[218:221], v[98:101]
	v_mfma_f32_16x16x32_bf16 v[90:93], v[234:237], v[226:229], v[90:93]
	v_mfma_f32_16x16x32_bf16 v[82:85], v[242:245], v[226:229], v[82:85]
	s_setprio 0
	s_mov_b32 m0, s3
	v_lshl_add_u64 v[248:249], s[28:29], 0, v[162:163]
	s_barrier
	ds_read_b128 v[172:175], v180 offset:16384
	ds_read_b128 v[182:185], v180 offset:17408
	ds_read_b128 v[206:209], v180 offset:18432
	ds_read_b128 v[210:213], v180 offset:19456
	ds_read_b128 v[214:217], v180 offset:20480
	ds_read_b128 v[218:221], v180 offset:21504
	ds_read_b128 v[222:225], v180 offset:22528
	ds_read_b128 v[226:229], v180 offset:23552
	global_load_lds_dwordx4 v[248:249], off
	v_lshl_add_u64 v[250:251], s[28:29], 0, v[164:165]
	s_mov_b32 m0, s56
	s_nop 0
	global_load_lds_dwordx4 v[250:251], off
	s_barrier
	s_waitcnt lgkmcnt(0)
	s_setprio 1
	v_mfma_f32_16x16x32_bf16 v[70:73], v[58:61], v[172:175], v[70:73]
	v_mfma_f32_16x16x32_bf16 v[54:57], v[74:77], v[172:175], v[54:57]
	v_mfma_f32_16x16x32_bf16 v[46:49], v[58:61], v[206:209], v[46:49]
	v_mfma_f32_16x16x32_bf16 v[38:41], v[74:77], v[206:209], v[38:41]
	v_mfma_f32_16x16x32_bf16 v[30:33], v[58:61], v[214:217], v[30:33]
	v_mfma_f32_16x16x32_bf16 v[22:25], v[74:77], v[214:217], v[22:25]
	v_mfma_f32_16x16x32_bf16 v[14:17], v[58:61], v[222:225], v[14:17]
	v_mfma_f32_16x16x32_bf16 v[6:9], v[74:77], v[222:225], v[6:9]
	v_mfma_f32_16x16x32_bf16 v[70:73], v[66:69], v[182:185], v[70:73]
	v_mfma_f32_16x16x32_bf16 v[54:57], v[78:81], v[182:185], v[54:57]
	v_mfma_f32_16x16x32_bf16 v[46:49], v[66:69], v[210:213], v[46:49]
	v_mfma_f32_16x16x32_bf16 v[38:41], v[78:81], v[210:213], v[38:41]
	v_mfma_f32_16x16x32_bf16 v[30:33], v[66:69], v[218:221], v[30:33]
	v_mfma_f32_16x16x32_bf16 v[22:25], v[78:81], v[218:221], v[22:25]
	v_mfma_f32_16x16x32_bf16 v[14:17], v[66:69], v[226:229], v[14:17]
	v_mfma_f32_16x16x32_bf16 v[6:9], v[78:81], v[226:229], v[6:9]
	s_setprio 0
	s_barrier
	s_add_u32 s64, s22, 0x40000
	s_addc_u32 s65, s23, 0
	s_add_i32 s63, s66, s37
	v_lshl_add_u64 v[58:59], s[64:65], 0, v[0:1]
	s_mov_b32 m0, s63
	s_nop 0
	global_load_lds_dwordx4 v[58:59], off
	v_lshl_add_u64 v[58:59], s[64:65], 0, v[166:167]
	s_add_i32 m0, s63, 0x2000
	s_nop 0
	global_load_lds_dwordx4 v[58:59], off
	s_waitcnt vmcnt(6)
	s_barrier
	s_setprio 1
	v_mfma_f32_16x16x32_bf16 v[50:53], v[238:241], v[172:175], v[50:53]
	v_mfma_f32_16x16x32_bf16 v[42:45], v[230:233], v[206:209], v[42:45]
	v_mfma_f32_16x16x32_bf16 v[34:37], v[238:241], v[206:209], v[34:37]
	v_mfma_f32_16x16x32_bf16 v[26:29], v[230:233], v[214:217], v[26:29]
	v_mfma_f32_16x16x32_bf16 v[18:21], v[238:241], v[214:217], v[18:21]
	v_mfma_f32_16x16x32_bf16 v[10:13], v[230:233], v[222:225], v[10:13]
	v_mfma_f32_16x16x32_bf16 v[2:5], v[238:241], v[222:225], v[2:5]
	v_mfma_f32_16x16x32_bf16 v[58:61], v[230:233], v[172:175], v[62:65]
	v_mfma_f32_16x16x32_bf16 v[50:53], v[242:245], v[182:185], v[50:53]
	v_mfma_f32_16x16x32_bf16 v[42:45], v[234:237], v[210:213], v[42:45]
	v_mfma_f32_16x16x32_bf16 v[34:37], v[242:245], v[210:213], v[34:37]
	v_mfma_f32_16x16x32_bf16 v[26:29], v[234:237], v[218:221], v[26:29]
	v_mfma_f32_16x16x32_bf16 v[18:21], v[242:245], v[218:221], v[18:21]
	v_mfma_f32_16x16x32_bf16 v[10:13], v[234:237], v[226:229], v[10:13]
	v_mfma_f32_16x16x32_bf16 v[2:5], v[242:245], v[226:229], v[2:5]
	v_mfma_f32_16x16x32_bf16 v[58:61], v[234:237], v[182:185], v[58:61]
	s_setprio 0
	s_add_i32 s63, 0, 0x18000
	v_add_u32_e32 v78, s63, v178
	s_barrier
	ds_read_b128 v[62:65], v78
	ds_read_b128 v[66:69], v78 offset:1024
	ds_read_b128 v[74:77], v78 offset:2048
	ds_read_b128 v[78:81], v78 offset:3072
	s_add_u32 s28, s28, 0x40000
	s_addc_u32 s29, s29, 0
	s_mov_b32 m0, s57
	v_lshl_add_u64 v[230:231], s[28:29], 0, v[162:163]
	ds_read_b128 v[172:175], v180 offset:32768
	ds_read_b128 v[182:185], v180 offset:33792
	ds_read_b128 v[206:209], v180 offset:34816
	ds_read_b128 v[210:213], v180 offset:35840
	ds_read_b128 v[214:217], v180 offset:36864
	ds_read_b128 v[218:221], v180 offset:37888
	ds_read_b128 v[222:225], v180 offset:38912
	ds_read_b128 v[226:229], v180 offset:39936
	global_load_lds_dwordx4 v[230:231], off
	v_lshl_add_u64 v[230:231], s[28:29], 0, v[164:165]
	s_mov_b32 m0, s58
	s_nop 0
	global_load_lds_dwordx4 v[230:231], off
	s_waitcnt lgkmcnt(8)
	s_barrier
	s_waitcnt lgkmcnt(0)
	s_setprio 1
	v_mfma_f32_16x16x32_bf16 v[142:145], v[62:65], v[172:175], v[142:145]
	v_mfma_f32_16x16x32_bf16 v[138:141], v[74:77], v[172:175], v[138:141]
	v_mfma_f32_16x16x32_bf16 v[126:129], v[62:65], v[206:209], v[126:129]
	v_mfma_f32_16x16x32_bf16 v[118:121], v[74:77], v[206:209], v[118:121]
	v_mfma_f32_16x16x32_bf16 v[110:113], v[62:65], v[214:217], v[110:113]
	v_mfma_f32_16x16x32_bf16 v[102:105], v[74:77], v[214:217], v[102:105]
	v_mfma_f32_16x16x32_bf16 v[94:97], v[62:65], v[222:225], v[94:97]
	v_mfma_f32_16x16x32_bf16 v[86:89], v[74:77], v[222:225], v[86:89]
	v_mfma_f32_16x16x32_bf16 v[142:145], v[66:69], v[182:185], v[142:145]
	v_mfma_f32_16x16x32_bf16 v[138:141], v[78:81], v[182:185], v[138:141]
	v_mfma_f32_16x16x32_bf16 v[126:129], v[66:69], v[210:213], v[126:129]
	v_mfma_f32_16x16x32_bf16 v[118:121], v[78:81], v[210:213], v[118:121]
	v_mfma_f32_16x16x32_bf16 v[110:113], v[66:69], v[218:221], v[110:113]
	v_mfma_f32_16x16x32_bf16 v[102:105], v[78:81], v[218:221], v[102:105]
	v_mfma_f32_16x16x32_bf16 v[94:97], v[66:69], v[226:229], v[94:97]
	v_mfma_f32_16x16x32_bf16 v[86:89], v[78:81], v[226:229], v[86:89]
	s_setprio 0
	s_barrier
	s_add_i32 s28, 0, 0x1c000
	s_add_i32 s29, s63, s37
	v_add_u32_e32 v181, s28, v178
	v_lshl_add_u64 v[186:187], v[186:187], 0, s[94:95]
	s_mov_b32 m0, s29
	ds_read_b128 v[230:233], v181
	ds_read_b128 v[234:237], v181 offset:1024
	ds_read_b128 v[238:241], v181 offset:2048
	ds_read_b128 v[242:245], v181 offset:3072
	global_load_lds_dwordx4 v[186:187], off
	v_lshl_add_u64 v[186:187], v[246:247], 0, s[94:95]
	s_add_i32 m0, s29, 0x2000
	s_nop 0
	global_load_lds_dwordx4 v[186:187], off
	s_barrier
	s_waitcnt lgkmcnt(0)
	s_setprio 1
	v_mfma_f32_16x16x32_bf16 v[134:137], v[230:233], v[172:175], v[134:137]
	v_mfma_f32_16x16x32_bf16 v[130:133], v[238:241], v[172:175], v[130:133]
	v_mfma_f32_16x16x32_bf16 v[122:125], v[230:233], v[206:209], v[122:125]
	v_mfma_f32_16x16x32_bf16 v[114:117], v[238:241], v[206:209], v[114:117]
	v_mfma_f32_16x16x32_bf16 v[106:109], v[230:233], v[214:217], v[106:109]
	v_mfma_f32_16x16x32_bf16 v[98:101], v[238:241], v[214:217], v[98:101]
	v_mfma_f32_16x16x32_bf16 v[90:93], v[230:233], v[222:225], v[90:93]
	v_mfma_f32_16x16x32_bf16 v[82:85], v[238:241], v[222:225], v[82:85]
	v_mfma_f32_16x16x32_bf16 v[134:137], v[234:237], v[182:185], v[134:137]
	v_mfma_f32_16x16x32_bf16 v[130:133], v[242:245], v[182:185], v[130:133]
	v_mfma_f32_16x16x32_bf16 v[122:125], v[234:237], v[210:213], v[122:125]
	v_mfma_f32_16x16x32_bf16 v[114:117], v[242:245], v[210:213], v[114:117]
	v_mfma_f32_16x16x32_bf16 v[106:109], v[234:237], v[218:221], v[106:109]
	v_mfma_f32_16x16x32_bf16 v[98:101], v[242:245], v[218:221], v[98:101]
	v_mfma_f32_16x16x32_bf16 v[90:93], v[234:237], v[226:229], v[90:93]
	v_mfma_f32_16x16x32_bf16 v[82:85], v[242:245], v[226:229], v[82:85]
	s_setprio 0
	s_mov_b32 m0, s59
	v_lshl_add_u64 v[186:187], v[248:249], 0, s[94:95]
	s_barrier
	ds_read_b128 v[172:175], v180 offset:49152
	ds_read_b128 v[182:185], v180 offset:50176
	ds_read_b128 v[206:209], v180 offset:51200
	ds_read_b128 v[210:213], v180 offset:52224
	ds_read_b128 v[214:217], v180 offset:53248
	ds_read_b128 v[218:221], v180 offset:54272
	ds_read_b128 v[222:225], v180 offset:55296
	ds_read_b128 v[226:229], v180 offset:56320
	global_load_lds_dwordx4 v[186:187], off
	v_lshl_add_u64 v[186:187], v[250:251], 0, s[94:95]
	s_mov_b32 m0, s60
	s_nop 0
	global_load_lds_dwordx4 v[186:187], off
	s_barrier
	s_waitcnt lgkmcnt(0)
	s_setprio 1
	v_mfma_f32_16x16x32_bf16 v[70:73], v[62:65], v[172:175], v[70:73]
	v_mfma_f32_16x16x32_bf16 v[54:57], v[74:77], v[172:175], v[54:57]
	v_mfma_f32_16x16x32_bf16 v[46:49], v[62:65], v[206:209], v[46:49]
	v_mfma_f32_16x16x32_bf16 v[38:41], v[74:77], v[206:209], v[38:41]
	v_mfma_f32_16x16x32_bf16 v[30:33], v[62:65], v[214:217], v[30:33]
	v_mfma_f32_16x16x32_bf16 v[22:25], v[74:77], v[214:217], v[22:25]
	v_mfma_f32_16x16x32_bf16 v[14:17], v[62:65], v[222:225], v[14:17]
	v_mfma_f32_16x16x32_bf16 v[6:9], v[74:77], v[222:225], v[6:9]
	v_mfma_f32_16x16x32_bf16 v[70:73], v[66:69], v[182:185], v[70:73]
	v_mfma_f32_16x16x32_bf16 v[54:57], v[78:81], v[182:185], v[54:57]
	v_mfma_f32_16x16x32_bf16 v[46:49], v[66:69], v[210:213], v[46:49]
	v_mfma_f32_16x16x32_bf16 v[38:41], v[78:81], v[210:213], v[38:41]
	v_mfma_f32_16x16x32_bf16 v[30:33], v[66:69], v[218:221], v[30:33]
	v_mfma_f32_16x16x32_bf16 v[22:25], v[78:81], v[218:221], v[22:25]
	v_mfma_f32_16x16x32_bf16 v[14:17], v[66:69], v[226:229], v[14:17]
	v_mfma_f32_16x16x32_bf16 v[6:9], v[78:81], v[226:229], v[6:9]
	s_setprio 0
	s_barrier
	s_add_u32 s22, s22, 0x40080
	s_addc_u32 s23, s23, 0
	s_add_i32 s28, s28, s37
	v_lshl_add_u64 v[62:63], s[22:23], 0, v[0:1]
	s_mov_b32 m0, s28
	s_nop 0
	global_load_lds_dwordx4 v[62:63], off
	v_lshl_add_u64 v[62:63], s[22:23], 0, v[166:167]
	s_add_i32 m0, s28, 0x2000
	s_nop 0
	global_load_lds_dwordx4 v[62:63], off
	s_waitcnt vmcnt(6)
	s_barrier
	s_setprio 1
	v_mfma_f32_16x16x32_bf16 v[58:61], v[230:233], v[172:175], v[58:61]
	v_mfma_f32_16x16x32_bf16 v[50:53], v[238:241], v[172:175], v[50:53]
	v_mfma_f32_16x16x32_bf16 v[42:45], v[230:233], v[206:209], v[42:45]
	v_mfma_f32_16x16x32_bf16 v[34:37], v[238:241], v[206:209], v[34:37]
	v_mfma_f32_16x16x32_bf16 v[26:29], v[230:233], v[214:217], v[26:29]
	v_mfma_f32_16x16x32_bf16 v[18:21], v[238:241], v[214:217], v[18:21]
	v_mfma_f32_16x16x32_bf16 v[10:13], v[230:233], v[222:225], v[10:13]
	v_mfma_f32_16x16x32_bf16 v[2:5], v[238:241], v[222:225], v[2:5]
	v_mfma_f32_16x16x32_bf16 v[62:65], v[234:237], v[182:185], v[58:61]
	v_mfma_f32_16x16x32_bf16 v[50:53], v[242:245], v[182:185], v[50:53]
	v_mfma_f32_16x16x32_bf16 v[42:45], v[234:237], v[210:213], v[42:45]
	v_mfma_f32_16x16x32_bf16 v[34:37], v[242:245], v[210:213], v[34:37]
	v_mfma_f32_16x16x32_bf16 v[26:29], v[234:237], v[218:221], v[26:29]
	v_mfma_f32_16x16x32_bf16 v[18:21], v[242:245], v[218:221], v[18:21]
	v_mfma_f32_16x16x32_bf16 v[10:13], v[234:237], v[226:229], v[10:13]
	v_mfma_f32_16x16x32_bf16 v[2:5], v[242:245], v[226:229], v[2:5]
	s_setprio 0
	s_add_i32 s49, s49, 2
	s_add_u32 s8, s8, 0x100
	s_addc_u32 s9, s9, 0
	s_add_u32 s31, s31, 0x100
	s_addc_u32 s47, s47, 0
	s_cmp_gt_u32 s49, 13
	s_barrier
	s_cbranch_scc0 .LBB0_95
	v_lshl_or_b32 v172, s24, 7, v179
	v_ashrrev_i32_e32 v173, 31, v172
	v_lshlrev_b64 v[58:59], 2, v[172:173]
	v_lshl_add_u64 v[60:61], s[40:41], 0, v[58:59]
	v_lshl_add_u64 v[74:75], s[44:45], 0, v[58:59]
	global_load_dwordx4 v[66:69], v[60:61], off offset:16
	global_load_dwordx4 v[78:81], v[60:61], off
	s_nop 0
	global_load_dwordx4 v[58:61], v[74:75], off offset:16
	s_nop 0
	global_load_dwordx4 v[74:77], v[74:75], off
	v_lshl_add_u32 v174, s2, 8, v177
	v_ashrrev_i32_e32 v175, 31, v174
	v_lshl_add_u64 v[172:173], v[172:173], 1, s[20:21]
	v_lshlrev_b64 v[182:183], 11, v[174:175]
	s_mov_b32 s2, 0x50000
	s_mov_b32 s24, s46
	s_mov_b64 s[22:23], s[54:55]
	s_mov_b64 s[8:9], s[50:51]
	s_waitcnt vmcnt(0)
	v_add_f32_e32 v138, v138, v66
	v_add_f32_e32 v126, v126, v78
	v_add_f32_e32 v130, v130, v58
	v_mul_f32_e32 v130, 0xbfb8aa3b, v130
	v_add_f32_e32 v131, v131, v59
	v_add_f32_e32 v122, v122, v74
	v_exp_f32_e32 v130, v130
	v_mul_f32_e32 v131, 0xbfb8aa3b, v131
	v_mul_f32_e32 v122, 0xbfb8aa3b, v122
	v_add_f32_e32 v123, v123, v75
	v_exp_f32_e32 v131, v131
	v_exp_f32_e32 v122, v122
	v_mul_f32_e32 v123, 0xbfb8aa3b, v123
	v_add_f32_e32 v124, v124, v76
	v_exp_f32_e32 v123, v123
	v_mul_f32_e32 v124, 0xbfb8aa3b, v124
	v_add_f32_e32 v125, v125, v77
	v_add_f32_e32 v114, v114, v58
	v_exp_f32_e32 v124, v124
	v_mul_f32_e32 v125, 0xbfb8aa3b, v125
	v_mul_f32_e32 v114, 0xbfb8aa3b, v114
	v_add_f32_e32 v115, v115, v59
	v_add_f32_e32 v106, v106, v74
	v_add_f32_e32 v130, 1.0, v130
	v_exp_f32_e32 v125, v125
	v_exp_f32_e32 v114, v114
	v_mul_f32_e32 v115, 0xbfb8aa3b, v115
	v_mul_f32_e32 v106, 0xbfb8aa3b, v106
	v_add_f32_e32 v107, v107, v75
	v_rcp_f32_e32 v130, v130
	v_add_f32_e32 v131, 1.0, v131
	v_add_f32_e32 v122, 1.0, v122
	v_exp_f32_e32 v115, v115
	v_exp_f32_e32 v106, v106
	v_mul_f32_e32 v107, 0xbfb8aa3b, v107
	v_add_f32_e32 v108, v108, v76
	v_rcp_f32_e32 v131, v131
	v_rcp_f32_e32 v122, v122
	v_add_f32_e32 v123, 1.0, v123
	v_exp_f32_e32 v107, v107
	v_mul_f32_e32 v108, 0xbfb8aa3b, v108
	v_add_f32_e32 v109, v109, v77
	v_add_f32_e32 v98, v98, v58
	v_rcp_f32_e32 v123, v123
	v_add_f32_e32 v124, 1.0, v124
	v_exp_f32_e32 v108, v108
	v_mul_f32_e32 v109, 0xbfb8aa3b, v109
	v_mul_f32_e32 v98, 0xbfb8aa3b, v98
	v_add_f32_e32 v99, v99, v59
	v_add_f32_e32 v90, v90, v74
	v_rcp_f32_e32 v124, v124
	v_add_f32_e32 v125, 1.0, v125
	v_add_f32_e32 v114, 1.0, v114
	v_exp_f32_e32 v109, v109
	v_exp_f32_e32 v98, v98
	v_mul_f32_e32 v99, 0xbfb8aa3b, v99
	v_mul_f32_e32 v90, 0xbfb8aa3b, v90
	v_add_f32_e32 v91, v91, v75
	v_mul_f32_e32 v138, v138, v130
	v_add_f32_e32 v130, v139, v67
	v_rcp_f32_e32 v125, v125
	v_rcp_f32_e32 v114, v114
	v_add_f32_e32 v115, 1.0, v115
	v_add_f32_e32 v106, 1.0, v106
	v_exp_f32_e32 v99, v99
	v_exp_f32_e32 v90, v90
	v_mul_f32_e32 v91, 0xbfb8aa3b, v91
	v_add_f32_e32 v92, v92, v76
	v_mul_f32_e32 v139, v130, v131
	v_add_f32_e32 v131, v132, v60
	v_mul_f32_e32 v122, v126, v122
	v_add_f32_e32 v126, v127, v79
	v_rcp_f32_e32 v115, v115
	v_rcp_f32_e32 v106, v106
	v_add_f32_e32 v107, 1.0, v107
	v_exp_f32_e32 v91, v91
	v_mul_f32_e32 v92, 0xbfb8aa3b, v92
	v_add_f32_e32 v93, v93, v77
	v_add_f32_e32 v82, v82, v58
	v_mul_f32_e32 v131, 0xbfb8aa3b, v131
	v_mul_f32_e32 v123, v126, v123
	v_add_f32_e32 v126, v128, v80
	v_rcp_f32_e32 v107, v107
	v_add_f32_e32 v108, 1.0, v108
	v_exp_f32_e32 v92, v92
	v_mul_f32_e32 v93, 0xbfb8aa3b, v93
	v_mul_f32_e32 v82, 0xbfb8aa3b, v82
	v_add_f32_e32 v83, v83, v59
	v_add_f32_e32 v50, v50, v58
	v_exp_f32_e32 v131, v131
	v_mul_f32_e32 v124, v126, v124
	v_add_f32_e32 v126, v129, v81
	v_add_f32_e32 v118, v118, v66
	v_rcp_f32_e32 v108, v108
	v_add_f32_e32 v109, 1.0, v109
	v_add_f32_e32 v98, 1.0, v98
	v_exp_f32_e32 v93, v93
	v_exp_f32_e32 v82, v82
	v_mul_f32_e32 v83, 0xbfb8aa3b, v83
	v_mul_f32_e32 v50, 0xbfb8aa3b, v50
	v_add_f32_e32 v51, v51, v59
	v_mul_f32_e32 v125, v126, v125
	v_mul_f32_e32 v126, v118, v114
	v_add_f32_e32 v114, v119, v67
	v_add_f32_e32 v110, v110, v78
	v_rcp_f32_e32 v109, v109
	v_rcp_f32_e32 v98, v98
	v_add_f32_e32 v99, 1.0, v99
	v_add_f32_e32 v90, 1.0, v90
	v_exp_f32_e32 v83, v83
	v_exp_f32_e32 v50, v50
	v_mul_f32_e32 v51, 0xbfb8aa3b, v51
	v_add_f32_e32 v34, v34, v58
	v_mul_f32_e32 v127, v114, v115
	v_add_f32_e32 v115, v116, v60
	v_mul_f32_e32 v106, v110, v106
	v_add_f32_e32 v110, v111, v79
	v_rcp_f32_e32 v99, v99
	v_rcp_f32_e32 v90, v90
	v_add_f32_e32 v91, 1.0, v91
	v_exp_f32_e32 v51, v51
	v_mul_f32_e32 v34, 0xbfb8aa3b, v34
	v_add_f32_e32 v35, v35, v59
	v_mul_f32_e32 v115, 0xbfb8aa3b, v115
	v_mul_f32_e32 v107, v110, v107
	v_add_f32_e32 v110, v112, v80
	v_rcp_f32_e32 v91, v91
	v_add_f32_e32 v92, 1.0, v92
	v_exp_f32_e32 v34, v34
	v_mul_f32_e32 v35, 0xbfb8aa3b, v35
	v_add_f32_e32 v18, v18, v58
	v_add_f32_e32 v131, 1.0, v131
	v_exp_f32_e32 v115, v115
	v_mul_f32_e32 v108, v110, v108
	v_add_f32_e32 v110, v113, v81
	v_add_f32_e32 v102, v102, v66
	v_rcp_f32_e32 v92, v92
	v_add_f32_e32 v93, 1.0, v93
	v_add_f32_e32 v82, 1.0, v82
	v_exp_f32_e32 v35, v35
	v_mul_f32_e32 v18, 0xbfb8aa3b, v18
	v_add_f32_e32 v19, v19, v59
	v_rcp_f32_e32 v131, v131
	v_mul_f32_e32 v109, v110, v109
	v_mul_f32_e32 v110, v102, v98
	v_add_f32_e32 v98, v103, v67
	v_add_f32_e32 v94, v94, v78
	v_rcp_f32_e32 v93, v93
	v_rcp_f32_e32 v82, v82
	v_add_f32_e32 v83, 1.0, v83
	v_add_f32_e32 v50, 1.0, v50
	v_exp_f32_e32 v18, v18
	v_mul_f32_e32 v19, 0xbfb8aa3b, v19
	v_add_f32_e32 v2, v2, v58
	v_mul_f32_e32 v111, v98, v99
	v_add_f32_e32 v99, v100, v60
	v_mul_f32_e32 v90, v94, v90
	v_add_f32_e32 v94, v95, v79
	v_rcp_f32_e32 v83, v83
	v_rcp_f32_e32 v50, v50
	v_add_f32_e32 v51, 1.0, v51
	v_exp_f32_e32 v19, v19
	v_mul_f32_e32 v2, 0xbfb8aa3b, v2
	v_add_f32_e32 v3, v3, v59
	v_add_f32_e32 v134, v134, v74
	v_mul_f32_e32 v99, 0xbfb8aa3b, v99
	v_mul_f32_e32 v91, v94, v91
	v_add_f32_e32 v94, v96, v80
	v_rcp_f32_e32 v51, v51
	v_add_f32_e32 v34, 1.0, v34
	v_exp_f32_e32 v2, v2
	v_mul_f32_e32 v3, 0xbfb8aa3b, v3
	v_mul_f32_e32 v134, 0xbfb8aa3b, v134
	v_add_f32_e32 v135, v135, v75
	v_add_f32_e32 v130, v140, v68
	v_add_f32_e32 v115, 1.0, v115
	v_exp_f32_e32 v99, v99
	v_mul_f32_e32 v92, v94, v92
	v_add_f32_e32 v94, v97, v81
	v_add_f32_e32 v86, v86, v66
	v_rcp_f32_e32 v34, v34
	v_add_f32_e32 v35, 1.0, v35
	v_exp_f32_e32 v3, v3
	v_exp_f32_e32 v134, v134
	v_mul_f32_e32 v135, 0xbfb8aa3b, v135
	v_add_f32_e32 v136, v136, v76
	v_mul_f32_e32 v140, v130, v131
	v_add_f32_e32 v131, v133, v61
	v_rcp_f32_e32 v115, v115
	v_mul_f32_e32 v93, v94, v93
	v_mul_f32_e32 v94, v86, v82
	v_add_f32_e32 v82, v87, v67
	v_add_f32_e32 v54, v54, v66
	v_rcp_f32_e32 v35, v35
	v_add_f32_e32 v18, 1.0, v18
	v_exp_f32_e32 v135, v135
	v_mul_f32_e32 v136, 0xbfb8aa3b, v136
	v_add_f32_e32 v137, v137, v77
	v_mul_f32_e32 v131, 0xbfb8aa3b, v131
	v_mul_f32_e32 v95, v82, v83
	v_add_f32_e32 v83, v84, v60
	v_mul_f32_e32 v54, v54, v50
	v_add_f32_e32 v50, v55, v67
	v_rcp_f32_e32 v18, v18
	v_add_f32_e32 v19, 1.0, v19
	v_exp_f32_e32 v136, v136
	v_mul_f32_e32 v137, 0xbfb8aa3b, v137
	v_exp_f32_e32 v131, v131
	v_mul_f32_e32 v83, 0xbfb8aa3b, v83
	v_mul_f32_e32 v55, v50, v51
	v_add_f32_e32 v51, v52, v60
	v_add_f32_e32 v38, v38, v66
	v_rcp_f32_e32 v19, v19
	v_add_f32_e32 v2, 1.0, v2
	v_exp_f32_e32 v137, v137
	v_add_f32_e32 v114, v120, v68
	v_add_f32_e32 v99, 1.0, v99
	v_exp_f32_e32 v83, v83
	v_mul_f32_e32 v51, 0xbfb8aa3b, v51
	v_mul_f32_e32 v38, v38, v34
	v_add_f32_e32 v34, v39, v67
	v_rcp_f32_e32 v2, v2
	v_add_f32_e32 v3, 1.0, v3
	v_add_f32_e32 v134, 1.0, v134
	v_mul_f32_e32 v120, v114, v115
	v_add_f32_e32 v115, v117, v61
	v_rcp_f32_e32 v99, v99
	v_exp_f32_e32 v51, v51
	v_mul_f32_e32 v39, v34, v35
	v_add_f32_e32 v35, v36, v60
	v_add_f32_e32 v22, v22, v66
	v_rcp_f32_e32 v3, v3
	v_rcp_f32_e32 v134, v134
	v_add_f32_e32 v135, 1.0, v135
	v_mul_f32_e32 v115, 0xbfb8aa3b, v115
	v_mul_f32_e32 v35, 0xbfb8aa3b, v35
	v_mul_f32_e32 v22, v22, v18
	v_add_f32_e32 v18, v23, v67
	v_rcp_f32_e32 v135, v135
	v_add_f32_e32 v136, 1.0, v136
	v_add_f32_e32 v131, 1.0, v131
	v_exp_f32_e32 v115, v115
	v_exp_f32_e32 v35, v35
	v_mul_f32_e32 v23, v18, v19
	v_add_f32_e32 v19, v20, v60
	v_add_f32_e32 v6, v6, v66
	v_rcp_f32_e32 v136, v136
	v_add_f32_e32 v137, 1.0, v137
	v_rcp_f32_e32 v131, v131
	v_add_f32_e32 v98, v104, v68
	v_add_f32_e32 v83, 1.0, v83
	v_mul_f32_e32 v19, 0xbfb8aa3b, v19
	v_mul_f32_e32 v6, v6, v2
	v_add_f32_e32 v2, v7, v67
	v_add_f32_e32 v142, v142, v78
	v_rcp_f32_e32 v137, v137
	v_mul_f32_e32 v104, v98, v99
	v_add_f32_e32 v99, v101, v61
	v_rcp_f32_e32 v83, v83
	v_add_f32_e32 v51, 1.0, v51
	v_exp_f32_e32 v19, v19
	v_mul_f32_e32 v7, v2, v3
	v_add_f32_e32 v3, v4, v60
	v_mul_f32_e32 v134, v142, v134
	v_add_f32_e32 v142, v143, v79
	v_mul_f32_e32 v99, 0xbfb8aa3b, v99
	v_rcp_f32_e32 v51, v51
	v_mul_f32_e32 v3, 0xbfb8aa3b, v3
	v_mul_f32_e32 v135, v142, v135
	v_add_f32_e32 v142, v144, v80
	v_add_f32_e32 v130, v141, v69
	v_add_f32_e32 v115, 1.0, v115
	v_exp_f32_e32 v99, v99
	v_add_f32_e32 v62, v62, v74
	v_add_f32_e32 v35, 1.0, v35
	v_exp_f32_e32 v3, v3
	v_mul_f32_e32 v136, v142, v136
	v_add_f32_e32 v142, v145, v81
	v_mul_f32_e32 v141, v130, v131
	v_lshl_add_u64 v[130:131], v[172:173], 0, v[182:183]
	v_cvt_pk_bf16_f32 v132, v134, v135
	v_rcp_f32_e32 v115, v115
	v_add_f32_e32 v82, v88, v68
	v_mul_f32_e32 v62, 0xbfb8aa3b, v62
	v_add_f32_e32 v63, v63, v75
	v_rcp_f32_e32 v35, v35
	v_mul_f32_e32 v137, v142, v137
	v_cvt_pk_bf16_f32 v133, v136, v137
	v_cvt_pk_bf16_f32 v134, v138, v139
	v_cvt_pk_bf16_f32 v135, v140, v141
	global_store_dwordx4 v[130:131], v[132:135], off
	v_mul_f32_e32 v88, v82, v83
	v_add_f32_e32 v83, v85, v61
	v_or_b32_e32 v132, 16, v174
	v_exp_f32_e32 v62, v62
	v_mul_f32_e32 v63, 0xbfb8aa3b, v63
	v_add_f32_e32 v64, v64, v76
	v_add_f32_e32 v50, v56, v68
	v_add_f32_e32 v42, v42, v74
	v_add_f32_e32 v19, 1.0, v19
	v_ashrrev_i32_e32 v133, 31, v132
	v_mul_f32_e32 v83, 0xbfb8aa3b, v83
	v_exp_f32_e32 v63, v63
	v_mul_f32_e32 v64, 0xbfb8aa3b, v64
	v_add_f32_e32 v65, v65, v77
	v_mul_f32_e32 v56, v50, v51
	v_add_f32_e32 v51, v53, v61
	v_mul_f32_e32 v42, 0xbfb8aa3b, v42
	v_add_f32_e32 v43, v43, v75
	v_rcp_f32_e32 v19, v19
	v_lshlrev_b64 v[132:133], 11, v[132:133]
	v_add_f32_e32 v114, v121, v69
	v_add_f32_e32 v99, 1.0, v99
	v_exp_f32_e32 v83, v83
	v_exp_f32_e32 v64, v64
	v_mul_f32_e32 v65, 0xbfb8aa3b, v65
	v_mul_f32_e32 v51, 0xbfb8aa3b, v51
	v_exp_f32_e32 v42, v42
	v_mul_f32_e32 v43, 0xbfb8aa3b, v43
	v_add_f32_e32 v44, v44, v76
	v_add_f32_e32 v34, v40, v68
	v_add_f32_e32 v26, v26, v74
	v_add_f32_e32 v3, 1.0, v3
	v_mul_f32_e32 v117, v114, v115
	v_lshl_add_u64 v[118:119], v[172:173], 0, v[132:133]
	v_cvt_pk_bf16_f32 v114, v122, v123
	v_rcp_f32_e32 v99, v99
	v_exp_f32_e32 v65, v65
	v_exp_f32_e32 v51, v51
	v_exp_f32_e32 v43, v43
	v_mul_f32_e32 v44, 0xbfb8aa3b, v44
	v_add_f32_e32 v45, v45, v77
	v_mul_f32_e32 v40, v34, v35
	v_add_f32_e32 v35, v37, v61
	v_mul_f32_e32 v26, 0xbfb8aa3b, v26
	v_add_f32_e32 v27, v27, v75
	v_rcp_f32_e32 v3, v3
	v_cvt_pk_bf16_f32 v115, v124, v125
	v_cvt_pk_bf16_f32 v116, v126, v127
	v_cvt_pk_bf16_f32 v117, v120, v117
	global_store_dwordx4 v[118:119], v[114:117], off
	v_add_f32_e32 v62, 1.0, v62
	v_exp_f32_e32 v44, v44
	v_or_b32_e32 v114, 32, v174
	v_mul_f32_e32 v45, 0xbfb8aa3b, v45
	v_mul_f32_e32 v35, 0xbfb8aa3b, v35
	v_exp_f32_e32 v26, v26
	v_mul_f32_e32 v27, 0xbfb8aa3b, v27
	v_add_f32_e32 v28, v28, v76
	v_add_f32_e32 v18, v24, v68
	v_add_f32_e32 v10, v10, v74
	v_ashrrev_i32_e32 v115, 31, v114
	v_rcp_f32_e32 v62, v62
	v_add_f32_e32 v63, 1.0, v63
	v_exp_f32_e32 v45, v45
	v_exp_f32_e32 v35, v35
	v_exp_f32_e32 v27, v27
	v_mul_f32_e32 v28, 0xbfb8aa3b, v28
	v_add_f32_e32 v29, v29, v77
	v_mul_f32_e32 v24, v18, v19
	v_add_f32_e32 v19, v21, v61
	v_mul_f32_e32 v10, 0xbfb8aa3b, v10
	v_add_f32_e32 v11, v11, v75
	v_lshlrev_b64 v[114:115], 11, v[114:115]
	v_add_f32_e32 v98, v105, v69
	v_add_f32_e32 v83, 1.0, v83
	v_rcp_f32_e32 v63, v63
	v_add_f32_e32 v64, 1.0, v64
	v_add_f32_e32 v42, 1.0, v42
	v_exp_f32_e32 v28, v28
	v_mul_f32_e32 v29, 0xbfb8aa3b, v29
	v_mul_f32_e32 v19, 0xbfb8aa3b, v19
	v_exp_f32_e32 v10, v10
	v_mul_f32_e32 v11, 0xbfb8aa3b, v11
	v_add_f32_e32 v12, v12, v76
	v_add_f32_e32 v2, v8, v68
	v_mul_f32_e32 v101, v98, v99
	v_lshl_add_u64 v[102:103], v[172:173], 0, v[114:115]
	v_cvt_pk_bf16_f32 v98, v106, v107
	v_rcp_f32_e32 v83, v83
	v_rcp_f32_e32 v64, v64
	v_add_f32_e32 v65, 1.0, v65
	v_add_f32_e32 v51, 1.0, v51
	v_rcp_f32_e32 v42, v42
	v_add_f32_e32 v43, 1.0, v43
	v_exp_f32_e32 v29, v29
	v_exp_f32_e32 v19, v19
	v_exp_f32_e32 v11, v11
	v_mul_f32_e32 v12, 0xbfb8aa3b, v12
	v_add_f32_e32 v13, v13, v77
	v_mul_f32_e32 v8, v2, v3
	v_add_f32_e32 v3, v5, v61
	v_cvt_pk_bf16_f32 v99, v108, v109
	v_cvt_pk_bf16_f32 v100, v110, v111
	v_cvt_pk_bf16_f32 v101, v104, v101
	global_store_dwordx4 v[102:103], v[98:101], off
	v_add_f32_e32 v70, v70, v78
	v_rcp_f32_e32 v65, v65
	v_or_b32_e32 v98, 48, v174
	v_rcp_f32_e32 v51, v51
	v_rcp_f32_e32 v43, v43
	v_add_f32_e32 v44, 1.0, v44
	v_add_f32_e32 v26, 1.0, v26
	v_exp_f32_e32 v12, v12
	v_mul_f32_e32 v13, 0xbfb8aa3b, v13
	v_mul_f32_e32 v3, 0xbfb8aa3b, v3
	v_ashrrev_i32_e32 v99, 31, v98
	v_mul_f32_e32 v62, v70, v62
	v_add_f32_e32 v70, v71, v79
	v_rcp_f32_e32 v44, v44
	v_add_f32_e32 v45, 1.0, v45
	v_add_f32_e32 v35, 1.0, v35
	v_rcp_f32_e32 v26, v26
	v_add_f32_e32 v27, 1.0, v27
	v_exp_f32_e32 v13, v13
	v_exp_f32_e32 v3, v3
	v_lshlrev_b64 v[98:99], 11, v[98:99]
	v_add_f32_e32 v82, v89, v69
	v_mul_f32_e32 v63, v70, v63
	v_add_f32_e32 v70, v72, v80
	v_add_f32_e32 v46, v46, v78
	v_rcp_f32_e32 v45, v45
	v_rcp_f32_e32 v35, v35
	v_rcp_f32_e32 v27, v27
	v_add_f32_e32 v28, 1.0, v28
	v_add_f32_e32 v10, 1.0, v10
	v_mul_f32_e32 v85, v82, v83
	v_lshl_add_u64 v[86:87], v[172:173], 0, v[98:99]
	v_mul_f32_e32 v64, v70, v64
	v_add_f32_e32 v70, v73, v81
	v_add_f32_e32 v50, v57, v69
	v_mul_f32_e32 v42, v46, v42
	v_add_f32_e32 v46, v47, v79
	v_rcp_f32_e32 v28, v28
	v_add_f32_e32 v29, 1.0, v29
	v_add_f32_e32 v19, 1.0, v19
	v_rcp_f32_e32 v10, v10
	v_add_f32_e32 v11, 1.0, v11
	v_cvt_pk_bf16_f32 v82, v90, v91
	v_cvt_pk_bf16_f32 v83, v92, v93
	v_cvt_pk_bf16_f32 v84, v94, v95
	v_cvt_pk_bf16_f32 v85, v88, v85
	global_store_dwordx4 v[86:87], v[82:85], off
	v_mul_f32_e32 v65, v70, v65
	v_mul_f32_e32 v53, v50, v51
	v_cvt_pk_bf16_f32 v50, v62, v63
	v_cvt_pk_bf16_f32 v51, v64, v65
	v_cvt_pk_bf16_f32 v52, v54, v55
	v_add_co_u32_e32 v54, vcc, s67, v130
	v_mul_f32_e32 v43, v46, v43
	v_add_f32_e32 v46, v48, v80
	v_add_f32_e32 v30, v30, v78
	v_rcp_f32_e32 v29, v29
	v_rcp_f32_e32 v19, v19
	v_rcp_f32_e32 v11, v11
	v_add_f32_e32 v12, 1.0, v12
	v_addc_co_u32_e32 v55, vcc, 0, v131, vcc
	v_mul_f32_e32 v44, v46, v44
	v_add_f32_e32 v46, v49, v81
	v_add_f32_e32 v34, v41, v69
	v_mul_f32_e32 v26, v30, v26
	v_add_f32_e32 v30, v31, v79
	v_rcp_f32_e32 v12, v12
	v_add_f32_e32 v13, 1.0, v13
	v_add_f32_e32 v3, 1.0, v3
	v_cvt_pk_bf16_f32 v53, v56, v53
	global_store_dwordx4 v[54:55], v[50:53], off
	v_mul_f32_e32 v45, v46, v45
	v_mul_f32_e32 v37, v34, v35
	v_cvt_pk_bf16_f32 v34, v42, v43
	v_cvt_pk_bf16_f32 v35, v44, v45
	v_cvt_pk_bf16_f32 v36, v38, v39
	v_add_co_u32_e32 v38, vcc, s68, v130
	v_mul_f32_e32 v27, v30, v27
	v_add_f32_e32 v30, v32, v80
	v_add_f32_e32 v14, v14, v78
	v_rcp_f32_e32 v13, v13
	v_rcp_f32_e32 v3, v3
	v_addc_co_u32_e32 v39, vcc, 0, v131, vcc
	v_mul_f32_e32 v28, v30, v28
	v_add_f32_e32 v30, v33, v81
	v_add_f32_e32 v18, v25, v69
	v_mul_f32_e32 v10, v14, v10
	v_add_f32_e32 v14, v15, v79
	v_cvt_pk_bf16_f32 v37, v40, v37
	global_store_dwordx4 v[38:39], v[34:37], off
	v_mul_f32_e32 v29, v30, v29
	v_mul_f32_e32 v21, v18, v19
	v_cvt_pk_bf16_f32 v18, v26, v27
	v_cvt_pk_bf16_f32 v19, v28, v29
	v_cvt_pk_bf16_f32 v20, v22, v23
	v_add_co_u32_e32 v22, vcc, s2, v130
	v_mul_f32_e32 v11, v14, v11
	v_add_f32_e32 v14, v16, v80
	v_addc_co_u32_e32 v23, vcc, 0, v131, vcc
	v_mul_f32_e32 v12, v14, v12
	v_add_f32_e32 v14, v17, v81
	v_add_f32_e32 v2, v9, v69
	v_cvt_pk_bf16_f32 v21, v24, v21
	global_store_dwordx4 v[22:23], v[18:21], off
	v_mul_f32_e32 v13, v14, v13
	v_mul_f32_e32 v5, v2, v3
	v_cvt_pk_bf16_f32 v2, v10, v11
	v_cvt_pk_bf16_f32 v3, v12, v13
	v_cvt_pk_bf16_f32 v4, v6, v7
	v_add_co_u32_e32 v6, vcc, 0x58000, v130
	s_mov_b32 s2, s48
	s_nop 0
	v_addc_co_u32_e32 v7, vcc, 0, v131, vcc
	s_and_b64 vcc, exec, s[38:39]
	v_cvt_pk_bf16_f32 v5, v8, v5
	global_store_dwordx4 v[6:7], v[2:5], off
	s_cbranch_vccz .LBB0_88
	s_waitcnt vmcnt(8)
	s_cmpk_gt_u32 s35, 0xff
	s_cbranch_scc1 .LBB0_99
	s_barrier

.LBB0_260:
	s_add_u32 s22, s0, 0xfffc0080
	s_addc_u32 s23, s1, -1
	s_add_i32 s60, 0, 0x10000
	v_add_u32_e32 v142, s60, v178
	ds_read_b128 v[130:133], v142
	ds_read_b128 v[134:137], v142 offset:1024
	ds_read_b128 v[138:141], v142 offset:2048
	ds_read_b128 v[142:145], v142 offset:3072
	s_cmp_eq_u32 s59, 12
	s_cselect_b32 s47, s35, s23
	s_cselect_b32 s46, s55, s22
	s_cselect_b32 s23, s31, s58
	s_cselect_b32 s22, s56, s57
	v_lshl_add_u64 v[186:187], s[0:1], 0, v[168:169]
	s_add_i32 m0, s27, 0xc000
	ds_read_b128 v[172:175], v180
	ds_read_b128 v[182:185], v180 offset:1024
	ds_read_b128 v[206:209], v180 offset:2048
	ds_read_b128 v[210:213], v180 offset:3072
	ds_read_b128 v[214:217], v180 offset:4096
	ds_read_b128 v[218:221], v180 offset:5120
	ds_read_b128 v[222:225], v180 offset:6144
	ds_read_b128 v[226:229], v180 offset:7168
	global_load_lds_dwordx4 v[186:187], off
	v_lshl_add_u64 v[186:187], s[0:1], 0, v[170:171]
	s_add_i32 m0, s27, 0xe000
	s_nop 0
	global_load_lds_dwordx4 v[186:187], off
	s_waitcnt lgkmcnt(8)
	s_barrier
	s_waitcnt lgkmcnt(0)
	s_setprio 1
	v_mfma_f32_16x16x32_bf16 v[126:129], v[130:133], v[172:175], v[126:129]
	v_mfma_f32_16x16x32_bf16 v[122:125], v[138:141], v[172:175], v[122:125]
	v_mfma_f32_16x16x32_bf16 v[110:113], v[130:133], v[206:209], v[110:113]
	v_mfma_f32_16x16x32_bf16 v[106:109], v[138:141], v[206:209], v[106:109]
	v_mfma_f32_16x16x32_bf16 v[94:97], v[130:133], v[214:217], v[94:97]
	v_mfma_f32_16x16x32_bf16 v[90:93], v[138:141], v[214:217], v[90:93]
	v_mfma_f32_16x16x32_bf16 v[78:81], v[130:133], v[222:225], v[78:81]
	v_mfma_f32_16x16x32_bf16 v[74:77], v[138:141], v[222:225], v[74:77]
	v_mfma_f32_16x16x32_bf16 v[126:129], v[134:137], v[182:185], v[126:129]
	v_mfma_f32_16x16x32_bf16 v[122:125], v[142:145], v[182:185], v[122:125]
	v_mfma_f32_16x16x32_bf16 v[110:113], v[134:137], v[210:213], v[110:113]
	v_mfma_f32_16x16x32_bf16 v[106:109], v[142:145], v[210:213], v[106:109]
	v_mfma_f32_16x16x32_bf16 v[94:97], v[134:137], v[218:221], v[94:97]
	v_mfma_f32_16x16x32_bf16 v[90:93], v[142:145], v[218:221], v[90:93]
	v_mfma_f32_16x16x32_bf16 v[78:81], v[134:137], v[226:229], v[78:81]
	v_mfma_f32_16x16x32_bf16 v[74:77], v[142:145], v[226:229], v[74:77]
	s_setprio 0
	s_barrier
	s_add_i32 s62, 0, 0x14000
	s_add_i32 s60, s60, s25
	v_add_u32_e32 v181, s62, v178
	v_lshl_add_u64 v[186:187], s[22:23], 0, v[0:1]
	s_mov_b32 m0, s60
	ds_read_b128 v[230:233], v181
	ds_read_b128 v[234:237], v181 offset:1024
	ds_read_b128 v[238:241], v181 offset:2048
	ds_read_b128 v[242:245], v181 offset:3072
	global_load_lds_dwordx4 v[186:187], off
	v_lshl_add_u64 v[246:247], s[22:23], 0, v[162:163]
	s_add_i32 m0, s60, 0x2000
	s_nop 0
	global_load_lds_dwordx4 v[246:247], off
	s_barrier
	s_waitcnt lgkmcnt(0)
	s_setprio 1
	v_mfma_f32_16x16x32_bf16 v[118:121], v[230:233], v[172:175], v[118:121]
	v_mfma_f32_16x16x32_bf16 v[114:117], v[238:241], v[172:175], v[114:117]
	v_mfma_f32_16x16x32_bf16 v[102:105], v[230:233], v[206:209], v[102:105]
	v_mfma_f32_16x16x32_bf16 v[98:101], v[238:241], v[206:209], v[98:101]
	v_mfma_f32_16x16x32_bf16 v[86:89], v[230:233], v[214:217], v[86:89]
	v_mfma_f32_16x16x32_bf16 v[82:85], v[238:241], v[214:217], v[82:85]
	v_mfma_f32_16x16x32_bf16 v[70:73], v[230:233], v[222:225], v[70:73]
	v_mfma_f32_16x16x32_bf16 v[66:69], v[238:241], v[222:225], v[66:69]
	v_mfma_f32_16x16x32_bf16 v[118:121], v[234:237], v[182:185], v[118:121]
	v_mfma_f32_16x16x32_bf16 v[114:117], v[242:245], v[182:185], v[114:117]
	v_mfma_f32_16x16x32_bf16 v[102:105], v[234:237], v[210:213], v[102:105]
	v_mfma_f32_16x16x32_bf16 v[98:101], v[242:245], v[210:213], v[98:101]
	v_mfma_f32_16x16x32_bf16 v[86:89], v[234:237], v[218:221], v[86:89]
	v_mfma_f32_16x16x32_bf16 v[82:85], v[242:245], v[218:221], v[82:85]
	v_mfma_f32_16x16x32_bf16 v[70:73], v[234:237], v[226:229], v[70:73]
	v_mfma_f32_16x16x32_bf16 v[66:69], v[242:245], v[226:229], v[66:69]
	s_setprio 0
	s_mov_b32 m0, s27
	v_lshl_add_u64 v[248:249], s[46:47], 0, v[166:167]
	s_barrier
	ds_read_b128 v[172:175], v180 offset:16384
	ds_read_b128 v[182:185], v180 offset:17408
	ds_read_b128 v[206:209], v180 offset:18432
	ds_read_b128 v[210:213], v180 offset:19456
	ds_read_b128 v[214:217], v180 offset:20480
	ds_read_b128 v[218:221], v180 offset:21504
	ds_read_b128 v[222:225], v180 offset:22528
	ds_read_b128 v[226:229], v180 offset:23552
	global_load_lds_dwordx4 v[248:249], off
	v_lshl_add_u64 v[250:251], s[46:47], 0, v[164:165]
	s_mov_b32 m0, s45
	s_nop 0
	global_load_lds_dwordx4 v[250:251], off
	s_barrier
	s_waitcnt lgkmcnt(0)
	s_setprio 1
	v_mfma_f32_16x16x32_bf16 v[62:65], v[130:133], v[172:175], v[62:65]
	v_mfma_f32_16x16x32_bf16 v[58:61], v[138:141], v[172:175], v[58:61]
	v_mfma_f32_16x16x32_bf16 v[50:53], v[130:133], v[206:209], v[50:53]
	v_mfma_f32_16x16x32_bf16 v[42:45], v[138:141], v[206:209], v[42:45]
	v_mfma_f32_16x16x32_bf16 v[34:37], v[130:133], v[214:217], v[34:37]
	v_mfma_f32_16x16x32_bf16 v[26:29], v[138:141], v[214:217], v[26:29]
	v_mfma_f32_16x16x32_bf16 v[18:21], v[130:133], v[222:225], v[18:21]
	v_mfma_f32_16x16x32_bf16 v[10:13], v[138:141], v[222:225], v[10:13]
	v_mfma_f32_16x16x32_bf16 v[62:65], v[134:137], v[182:185], v[62:65]
	v_mfma_f32_16x16x32_bf16 v[58:61], v[142:145], v[182:185], v[58:61]
	v_mfma_f32_16x16x32_bf16 v[50:53], v[134:137], v[210:213], v[50:53]
	v_mfma_f32_16x16x32_bf16 v[42:45], v[142:145], v[210:213], v[42:45]
	v_mfma_f32_16x16x32_bf16 v[34:37], v[134:137], v[218:221], v[34:37]
	v_mfma_f32_16x16x32_bf16 v[26:29], v[142:145], v[218:221], v[26:29]
	v_mfma_f32_16x16x32_bf16 v[18:21], v[134:137], v[226:229], v[18:21]
	v_mfma_f32_16x16x32_bf16 v[10:13], v[142:145], v[226:229], v[10:13]
	s_setprio 0
	s_barrier
	s_add_u32 s60, s22, 0x40000
	s_addc_u32 s61, s23, 0
	s_add_i32 s62, s62, s25
	v_lshl_add_u64 v[130:131], s[60:61], 0, v[0:1]
	s_mov_b32 m0, s62
	s_nop 0
	global_load_lds_dwordx4 v[130:131], off
	v_lshl_add_u64 v[130:131], s[60:61], 0, v[162:163]
	s_add_i32 m0, s62, 0x2000
	s_nop 0
	global_load_lds_dwordx4 v[130:131], off
	s_waitcnt vmcnt(6)
	s_barrier
	s_setprio 1
	v_mfma_f32_16x16x32_bf16 v[54:57], v[230:233], v[172:175], v[54:57]
	v_mfma_f32_16x16x32_bf16 v[46:49], v[238:241], v[172:175], v[46:49]
	v_mfma_f32_16x16x32_bf16 v[38:41], v[230:233], v[206:209], v[38:41]
	v_mfma_f32_16x16x32_bf16 v[30:33], v[238:241], v[206:209], v[30:33]
	v_mfma_f32_16x16x32_bf16 v[22:25], v[230:233], v[214:217], v[22:25]
	v_mfma_f32_16x16x32_bf16 v[14:17], v[238:241], v[214:217], v[14:17]
	v_mfma_f32_16x16x32_bf16 v[6:9], v[230:233], v[222:225], v[6:9]
	v_mfma_f32_16x16x32_bf16 v[2:5], v[238:241], v[222:225], v[2:5]
	v_mfma_f32_16x16x32_bf16 v[54:57], v[234:237], v[182:185], v[54:57]
	v_mfma_f32_16x16x32_bf16 v[46:49], v[242:245], v[182:185], v[46:49]
	v_mfma_f32_16x16x32_bf16 v[38:41], v[234:237], v[210:213], v[38:41]
	v_mfma_f32_16x16x32_bf16 v[30:33], v[242:245], v[210:213], v[30:33]
	v_mfma_f32_16x16x32_bf16 v[22:25], v[234:237], v[218:221], v[22:25]
	v_mfma_f32_16x16x32_bf16 v[14:17], v[242:245], v[218:221], v[14:17]
	v_mfma_f32_16x16x32_bf16 v[6:9], v[234:237], v[226:229], v[6:9]
	v_mfma_f32_16x16x32_bf16 v[2:5], v[242:245], v[226:229], v[2:5]
	s_setprio 0
	s_add_i32 s60, 0, 0x18000
	v_add_u32_e32 v142, s60, v178
	s_barrier
	ds_read_b128 v[130:133], v142
	ds_read_b128 v[134:137], v142 offset:1024
	ds_read_b128 v[138:141], v142 offset:2048
	ds_read_b128 v[142:145], v142 offset:3072
	s_add_u32 s46, s46, 0x40000
	s_addc_u32 s47, s47, 0
	s_mov_b32 m0, s48
	v_lshl_add_u64 v[230:231], s[46:47], 0, v[166:167]
	ds_read_b128 v[172:175], v180 offset:32768
	ds_read_b128 v[182:185], v180 offset:33792
	ds_read_b128 v[206:209], v180 offset:34816
	ds_read_b128 v[210:213], v180 offset:35840
	ds_read_b128 v[214:217], v180 offset:36864
	ds_read_b128 v[218:221], v180 offset:37888
	ds_read_b128 v[222:225], v180 offset:38912
	ds_read_b128 v[226:229], v180 offset:39936
	global_load_lds_dwordx4 v[230:231], off
	v_lshl_add_u64 v[230:231], s[46:47], 0, v[164:165]
	s_mov_b32 m0, s49
	s_nop 0
	global_load_lds_dwordx4 v[230:231], off
	s_waitcnt lgkmcnt(8)
	s_barrier
	s_waitcnt lgkmcnt(0)
	s_setprio 1
	v_mfma_f32_16x16x32_bf16 v[126:129], v[130:133], v[172:175], v[126:129]
	v_mfma_f32_16x16x32_bf16 v[122:125], v[138:141], v[172:175], v[122:125]
	v_mfma_f32_16x16x32_bf16 v[110:113], v[130:133], v[206:209], v[110:113]
	v_mfma_f32_16x16x32_bf16 v[106:109], v[138:141], v[206:209], v[106:109]
	v_mfma_f32_16x16x32_bf16 v[94:97], v[130:133], v[214:217], v[94:97]
	v_mfma_f32_16x16x32_bf16 v[90:93], v[138:141], v[214:217], v[90:93]
	v_mfma_f32_16x16x32_bf16 v[78:81], v[130:133], v[222:225], v[78:81]
	v_mfma_f32_16x16x32_bf16 v[74:77], v[138:141], v[222:225], v[74:77]
	v_mfma_f32_16x16x32_bf16 v[126:129], v[134:137], v[182:185], v[126:129]
	v_mfma_f32_16x16x32_bf16 v[122:125], v[142:145], v[182:185], v[122:125]
	v_mfma_f32_16x16x32_bf16 v[110:113], v[134:137], v[210:213], v[110:113]
	v_mfma_f32_16x16x32_bf16 v[106:109], v[142:145], v[210:213], v[106:109]
	v_mfma_f32_16x16x32_bf16 v[94:97], v[134:137], v[218:221], v[94:97]
	v_mfma_f32_16x16x32_bf16 v[90:93], v[142:145], v[218:221], v[90:93]
	v_mfma_f32_16x16x32_bf16 v[78:81], v[134:137], v[226:229], v[78:81]
	v_mfma_f32_16x16x32_bf16 v[74:77], v[142:145], v[226:229], v[74:77]
	s_setprio 0
	s_barrier
	s_add_i32 s46, 0, 0x1c000
	s_add_i32 s47, s60, s25
	v_add_u32_e32 v181, s46, v178
	v_lshl_add_u64 v[186:187], v[186:187], 0, s[94:95]
	s_mov_b32 m0, s47
	ds_read_b128 v[230:233], v181
	ds_read_b128 v[234:237], v181 offset:1024
	ds_read_b128 v[238:241], v181 offset:2048
	ds_read_b128 v[242:245], v181 offset:3072
	global_load_lds_dwordx4 v[186:187], off
	v_lshl_add_u64 v[186:187], v[246:247], 0, s[94:95]
	s_add_i32 m0, s47, 0x2000
	s_nop 0
	global_load_lds_dwordx4 v[186:187], off
	s_barrier
	s_waitcnt lgkmcnt(0)
	s_setprio 1
	v_mfma_f32_16x16x32_bf16 v[118:121], v[230:233], v[172:175], v[118:121]
	v_mfma_f32_16x16x32_bf16 v[114:117], v[238:241], v[172:175], v[114:117]
	v_mfma_f32_16x16x32_bf16 v[102:105], v[230:233], v[206:209], v[102:105]
	v_mfma_f32_16x16x32_bf16 v[98:101], v[238:241], v[206:209], v[98:101]
	v_mfma_f32_16x16x32_bf16 v[86:89], v[230:233], v[214:217], v[86:89]
	v_mfma_f32_16x16x32_bf16 v[82:85], v[238:241], v[214:217], v[82:85]
	v_mfma_f32_16x16x32_bf16 v[70:73], v[230:233], v[222:225], v[70:73]
	v_mfma_f32_16x16x32_bf16 v[66:69], v[238:241], v[222:225], v[66:69]
	v_mfma_f32_16x16x32_bf16 v[118:121], v[234:237], v[182:185], v[118:121]
	v_mfma_f32_16x16x32_bf16 v[114:117], v[242:245], v[182:185], v[114:117]
	v_mfma_f32_16x16x32_bf16 v[102:105], v[234:237], v[210:213], v[102:105]
	v_mfma_f32_16x16x32_bf16 v[98:101], v[242:245], v[210:213], v[98:101]
	v_mfma_f32_16x16x32_bf16 v[86:89], v[234:237], v[218:221], v[86:89]
	v_mfma_f32_16x16x32_bf16 v[82:85], v[242:245], v[218:221], v[82:85]
	v_mfma_f32_16x16x32_bf16 v[70:73], v[234:237], v[226:229], v[70:73]
	v_mfma_f32_16x16x32_bf16 v[66:69], v[242:245], v[226:229], v[66:69]
	s_setprio 0
	s_mov_b32 m0, s51
	v_lshl_add_u64 v[186:187], v[248:249], 0, s[94:95]
	s_barrier
	ds_read_b128 v[172:175], v180 offset:49152
	ds_read_b128 v[182:185], v180 offset:50176
	ds_read_b128 v[206:209], v180 offset:51200
	ds_read_b128 v[210:213], v180 offset:52224
	ds_read_b128 v[214:217], v180 offset:53248
	ds_read_b128 v[218:221], v180 offset:54272
	ds_read_b128 v[222:225], v180 offset:55296
	ds_read_b128 v[226:229], v180 offset:56320
	global_load_lds_dwordx4 v[186:187], off
	v_lshl_add_u64 v[186:187], v[250:251], 0, s[94:95]
	s_mov_b32 m0, s52
	s_nop 0
	global_load_lds_dwordx4 v[186:187], off
	s_barrier
	s_waitcnt lgkmcnt(0)
	s_setprio 1
	v_mfma_f32_16x16x32_bf16 v[62:65], v[130:133], v[172:175], v[62:65]
	v_mfma_f32_16x16x32_bf16 v[58:61], v[138:141], v[172:175], v[58:61]
	v_mfma_f32_16x16x32_bf16 v[50:53], v[130:133], v[206:209], v[50:53]
	v_mfma_f32_16x16x32_bf16 v[42:45], v[138:141], v[206:209], v[42:45]
	v_mfma_f32_16x16x32_bf16 v[34:37], v[130:133], v[214:217], v[34:37]
	v_mfma_f32_16x16x32_bf16 v[26:29], v[138:141], v[214:217], v[26:29]
	v_mfma_f32_16x16x32_bf16 v[18:21], v[130:133], v[222:225], v[18:21]
	v_mfma_f32_16x16x32_bf16 v[10:13], v[138:141], v[222:225], v[10:13]
	v_mfma_f32_16x16x32_bf16 v[62:65], v[134:137], v[182:185], v[62:65]
	v_mfma_f32_16x16x32_bf16 v[58:61], v[142:145], v[182:185], v[58:61]
	v_mfma_f32_16x16x32_bf16 v[50:53], v[134:137], v[210:213], v[50:53]
	v_mfma_f32_16x16x32_bf16 v[42:45], v[142:145], v[210:213], v[42:45]
	v_mfma_f32_16x16x32_bf16 v[34:37], v[134:137], v[218:221], v[34:37]
	v_mfma_f32_16x16x32_bf16 v[26:29], v[142:145], v[218:221], v[26:29]
	v_mfma_f32_16x16x32_bf16 v[18:21], v[134:137], v[226:229], v[18:21]
	v_mfma_f32_16x16x32_bf16 v[10:13], v[142:145], v[226:229], v[10:13]
	s_setprio 0
	s_barrier
	s_add_u32 s22, s22, 0x40080
	s_addc_u32 s23, s23, 0
	s_add_i32 s46, s46, s25
	v_lshl_add_u64 v[130:131], s[22:23], 0, v[0:1]
	s_mov_b32 m0, s46
	s_nop 0
	global_load_lds_dwordx4 v[130:131], off
	v_lshl_add_u64 v[130:131], s[22:23], 0, v[162:163]
	s_add_i32 m0, s46, 0x2000
	s_nop 0
	global_load_lds_dwordx4 v[130:131], off
	s_waitcnt vmcnt(6)
	s_barrier
	s_setprio 1
	v_mfma_f32_16x16x32_bf16 v[54:57], v[230:233], v[172:175], v[54:57]
	v_mfma_f32_16x16x32_bf16 v[46:49], v[238:241], v[172:175], v[46:49]
	v_mfma_f32_16x16x32_bf16 v[38:41], v[230:233], v[206:209], v[38:41]
	v_mfma_f32_16x16x32_bf16 v[30:33], v[238:241], v[206:209], v[30:33]
	v_mfma_f32_16x16x32_bf16 v[22:25], v[230:233], v[214:217], v[22:25]
	v_mfma_f32_16x16x32_bf16 v[14:17], v[238:241], v[214:217], v[14:17]
	v_mfma_f32_16x16x32_bf16 v[6:9], v[230:233], v[222:225], v[6:9]
	v_mfma_f32_16x16x32_bf16 v[2:5], v[238:241], v[222:225], v[2:5]
	v_mfma_f32_16x16x32_bf16 v[54:57], v[234:237], v[182:185], v[54:57]
	v_mfma_f32_16x16x32_bf16 v[46:49], v[242:245], v[182:185], v[46:49]
	v_mfma_f32_16x16x32_bf16 v[38:41], v[234:237], v[210:213], v[38:41]
	v_mfma_f32_16x16x32_bf16 v[30:33], v[242:245], v[210:213], v[30:33]
	v_mfma_f32_16x16x32_bf16 v[22:25], v[234:237], v[218:221], v[22:25]
	v_mfma_f32_16x16x32_bf16 v[14:17], v[242:245], v[218:221], v[14:17]
	v_mfma_f32_16x16x32_bf16 v[6:9], v[234:237], v[226:229], v[6:9]
	v_mfma_f32_16x16x32_bf16 v[2:5], v[242:245], v[226:229], v[2:5]
	s_setprio 0
	s_add_i32 s59, s59, 2
	s_add_u32 s0, s0, 0x100
	s_addc_u32 s1, s1, 0
	s_add_u32 s57, s57, 0x100
	s_addc_u32 s58, s58, 0
	s_cmp_gt_u32 s59, 13
	s_barrier
	s_cbranch_scc0 .LBB0_260
	v_lshl_or_b32 v172, s54, 8, v179
	v_ashrrev_i32_e32 v173, 31, v172
	v_cndmask_b32_e64 v131, 0, 1, s[2:3]
	v_lshl_add_u64 v[174:175], v[172:173], 2, s[8:9]
	v_mov_b32_e32 v130, 0
	v_cmp_ne_u32_e64 s[0:1], 1, v131
	s_andn2_b64 vcc, exec, s[2:3]
	v_mov_b32_e32 v134, 0
	v_mov_b32_e32 v135, 0
	v_mov_b32_e32 v136, 0
	v_mov_b32_e32 v137, 0
	s_cbranch_vccnz .LBB0_263
	global_load_dwordx4 v[134:137], v[174:175], off

.LBB0_331:
	s_add_u32 s22, s24, 0x100
	s_addc_u32 s23, s25, 0
	s_add_i32 s52, 0, 0x10000
	v_add_u32_e32 v140, s52, v144
	ds_read_b128 v[164:167], v140
	ds_read_b128 v[168:171], v140 offset:1024
	ds_read_b128 v[172:175], v140 offset:2048
	ds_read_b128 v[176:179], v140 offset:3072
	s_cmp_eq_u32 s51, 40
	s_cselect_b32 s29, s3, s23
	s_cselect_b32 s28, s2, s22
	s_cselect_b32 s27, s1, s41
	s_cselect_b32 s26, s0, s40
	v_lshl_add_u64 v[140:141], s[24:25], 0, v[136:137]
	s_add_i32 m0, s35, 0xc000
	ds_read_b128 v[180:183], v162
	ds_read_b128 v[184:187], v162 offset:1024
	ds_read_b128 v[206:209], v162 offset:2048
	ds_read_b128 v[210:213], v162 offset:3072
	ds_read_b128 v[214:217], v162 offset:4096
	ds_read_b128 v[218:221], v162 offset:5120
	ds_read_b128 v[222:225], v162 offset:6144
	ds_read_b128 v[226:229], v162 offset:7168
	global_load_lds_dwordx4 v[140:141], off
	v_lshl_add_u64 v[140:141], s[24:25], 0, v[138:139]
	s_add_i32 m0, s35, 0xe000
	s_nop 0
	global_load_lds_dwordx4 v[140:141], off
	s_waitcnt lgkmcnt(8)
	s_barrier
	s_waitcnt lgkmcnt(0)
	s_setprio 1
	v_mfma_f32_16x16x32_bf16 v[126:129], v[164:167], v[180:183], v[126:129]
	v_mfma_f32_16x16x32_bf16 v[122:125], v[172:175], v[180:183], v[122:125]
	v_mfma_f32_16x16x32_bf16 v[114:117], v[164:167], v[206:209], v[114:117]
	v_mfma_f32_16x16x32_bf16 v[106:109], v[172:175], v[206:209], v[106:109]
	v_mfma_f32_16x16x32_bf16 v[98:101], v[164:167], v[214:217], v[98:101]
	v_mfma_f32_16x16x32_bf16 v[90:93], v[172:175], v[214:217], v[90:93]
	v_mfma_f32_16x16x32_bf16 v[82:85], v[164:167], v[222:225], v[82:85]
	v_mfma_f32_16x16x32_bf16 v[74:77], v[172:175], v[222:225], v[74:77]
	v_mfma_f32_16x16x32_bf16 v[126:129], v[168:171], v[184:187], v[126:129]
	v_mfma_f32_16x16x32_bf16 v[122:125], v[176:179], v[184:187], v[122:125]
	v_mfma_f32_16x16x32_bf16 v[114:117], v[168:171], v[210:213], v[114:117]
	v_mfma_f32_16x16x32_bf16 v[106:109], v[176:179], v[210:213], v[106:109]
	v_mfma_f32_16x16x32_bf16 v[98:101], v[168:171], v[218:221], v[98:101]
	v_mfma_f32_16x16x32_bf16 v[90:93], v[176:179], v[218:221], v[90:93]
	v_mfma_f32_16x16x32_bf16 v[82:85], v[168:171], v[226:229], v[82:85]
	v_mfma_f32_16x16x32_bf16 v[74:77], v[176:179], v[226:229], v[74:77]
	s_setprio 0
	s_barrier
	s_add_i32 s53, 0, 0x14000
	v_add_u32_e32 v140, s53, v144
	s_add_i32 s24, s52, s31
	ds_read_b128 v[230:233], v140
	ds_read_b128 v[234:237], v140 offset:1024
	ds_read_b128 v[238:241], v140 offset:2048
	ds_read_b128 v[242:245], v140 offset:3072
	v_lshl_add_u64 v[140:141], s[26:27], 0, v[0:1]
	s_mov_b32 m0, s24
	v_lshl_add_u64 v[246:247], s[26:27], 0, v[130:131]
	global_load_lds_dwordx4 v[140:141], off
	s_add_i32 m0, s24, 0x2000
	s_nop 0
	global_load_lds_dwordx4 v[246:247], off
	s_barrier
	s_waitcnt lgkmcnt(0)
	s_setprio 1
	v_mfma_f32_16x16x32_bf16 v[118:121], v[230:233], v[180:183], v[118:121]
	v_mfma_f32_16x16x32_bf16 v[110:113], v[238:241], v[180:183], v[110:113]
	v_mfma_f32_16x16x32_bf16 v[102:105], v[230:233], v[206:209], v[102:105]
	v_mfma_f32_16x16x32_bf16 v[94:97], v[238:241], v[206:209], v[94:97]
	v_mfma_f32_16x16x32_bf16 v[86:89], v[230:233], v[214:217], v[86:89]
	v_mfma_f32_16x16x32_bf16 v[78:81], v[238:241], v[214:217], v[78:81]
	v_mfma_f32_16x16x32_bf16 v[70:73], v[230:233], v[222:225], v[70:73]
	v_mfma_f32_16x16x32_bf16 v[66:69], v[238:241], v[222:225], v[66:69]
	v_mfma_f32_16x16x32_bf16 v[118:121], v[234:237], v[184:187], v[118:121]
	v_mfma_f32_16x16x32_bf16 v[110:113], v[242:245], v[184:187], v[110:113]
	v_mfma_f32_16x16x32_bf16 v[102:105], v[234:237], v[210:213], v[102:105]
	v_mfma_f32_16x16x32_bf16 v[94:97], v[242:245], v[210:213], v[94:97]
	v_mfma_f32_16x16x32_bf16 v[86:89], v[234:237], v[218:221], v[86:89]
	v_mfma_f32_16x16x32_bf16 v[78:81], v[242:245], v[218:221], v[78:81]
	v_mfma_f32_16x16x32_bf16 v[70:73], v[234:237], v[226:229], v[70:73]
	v_mfma_f32_16x16x32_bf16 v[66:69], v[242:245], v[226:229], v[66:69]
	s_setprio 0
	s_mov_b32 m0, s35
	v_lshl_add_u64 v[248:249], s[28:29], 0, v[134:135]
	s_barrier
	ds_read_b128 v[180:183], v162 offset:16384
	ds_read_b128 v[184:187], v162 offset:17408
	ds_read_b128 v[206:209], v162 offset:18432
	ds_read_b128 v[210:213], v162 offset:19456
	ds_read_b128 v[214:217], v162 offset:20480
	ds_read_b128 v[218:221], v162 offset:21504
	ds_read_b128 v[222:225], v162 offset:22528
	ds_read_b128 v[226:229], v162 offset:23552
	global_load_lds_dwordx4 v[248:249], off
	v_lshl_add_u64 v[250:251], s[28:29], 0, v[132:133]
	s_mov_b32 m0, s36
	s_nop 0
	global_load_lds_dwordx4 v[250:251], off
	s_barrier
	s_waitcnt lgkmcnt(0)
	s_setprio 1
	v_mfma_f32_16x16x32_bf16 v[62:65], v[164:167], v[180:183], v[62:65]
	v_mfma_f32_16x16x32_bf16 v[58:61], v[172:175], v[180:183], v[58:61]
	v_mfma_f32_16x16x32_bf16 v[50:53], v[164:167], v[206:209], v[50:53]
	v_mfma_f32_16x16x32_bf16 v[42:45], v[172:175], v[206:209], v[42:45]
	v_mfma_f32_16x16x32_bf16 v[34:37], v[164:167], v[214:217], v[34:37]
	v_mfma_f32_16x16x32_bf16 v[26:29], v[172:175], v[214:217], v[26:29]
	v_mfma_f32_16x16x32_bf16 v[18:21], v[164:167], v[222:225], v[18:21]
	v_mfma_f32_16x16x32_bf16 v[10:13], v[172:175], v[222:225], v[10:13]
	v_mfma_f32_16x16x32_bf16 v[62:65], v[168:171], v[184:187], v[62:65]
	v_mfma_f32_16x16x32_bf16 v[58:61], v[176:179], v[184:187], v[58:61]
	v_mfma_f32_16x16x32_bf16 v[50:53], v[168:171], v[210:213], v[50:53]
	v_mfma_f32_16x16x32_bf16 v[42:45], v[176:179], v[210:213], v[42:45]
	v_mfma_f32_16x16x32_bf16 v[34:37], v[168:171], v[218:221], v[34:37]
	v_mfma_f32_16x16x32_bf16 v[26:29], v[176:179], v[218:221], v[26:29]
	v_mfma_f32_16x16x32_bf16 v[18:21], v[168:171], v[226:229], v[18:21]
	v_mfma_f32_16x16x32_bf16 v[10:13], v[176:179], v[226:229], v[10:13]
	s_setprio 0
	s_barrier
	s_add_u32 s24, s26, 0xb0000
	s_addc_u32 s25, s27, 0
	s_add_i32 s52, s53, s31
	v_lshl_add_u64 v[164:165], s[24:25], 0, v[0:1]
	s_mov_b32 m0, s52
	s_nop 0
	global_load_lds_dwordx4 v[164:165], off
	v_lshl_add_u64 v[164:165], s[24:25], 0, v[130:131]
	s_add_i32 m0, s52, 0x2000
	s_nop 0
	global_load_lds_dwordx4 v[164:165], off
	s_waitcnt vmcnt(6)
	s_barrier
	s_setprio 1
	v_mfma_f32_16x16x32_bf16 v[54:57], v[230:233], v[180:183], v[54:57]
	v_mfma_f32_16x16x32_bf16 v[46:49], v[238:241], v[180:183], v[46:49]
	v_mfma_f32_16x16x32_bf16 v[38:41], v[230:233], v[206:209], v[38:41]
	v_mfma_f32_16x16x32_bf16 v[30:33], v[238:241], v[206:209], v[30:33]
	v_mfma_f32_16x16x32_bf16 v[22:25], v[230:233], v[214:217], v[22:25]
	v_mfma_f32_16x16x32_bf16 v[14:17], v[238:241], v[214:217], v[14:17]
	v_mfma_f32_16x16x32_bf16 v[6:9], v[230:233], v[222:225], v[6:9]
	v_mfma_f32_16x16x32_bf16 v[2:5], v[238:241], v[222:225], v[2:5]
	v_mfma_f32_16x16x32_bf16 v[54:57], v[234:237], v[184:187], v[54:57]
	v_mfma_f32_16x16x32_bf16 v[46:49], v[242:245], v[184:187], v[46:49]
	v_mfma_f32_16x16x32_bf16 v[38:41], v[234:237], v[210:213], v[38:41]
	v_mfma_f32_16x16x32_bf16 v[30:33], v[242:245], v[210:213], v[30:33]
	v_mfma_f32_16x16x32_bf16 v[22:25], v[234:237], v[218:221], v[22:25]
	v_mfma_f32_16x16x32_bf16 v[14:17], v[242:245], v[218:221], v[14:17]
	v_mfma_f32_16x16x32_bf16 v[6:9], v[234:237], v[226:229], v[6:9]
	v_mfma_f32_16x16x32_bf16 v[2:5], v[242:245], v[226:229], v[2:5]
	s_setprio 0
	s_add_i32 s52, 0, 0x18000
	v_add_u32_e32 v163, s52, v144
	s_barrier
	ds_read_b128 v[164:167], v163
	ds_read_b128 v[168:171], v163 offset:1024
	ds_read_b128 v[172:175], v163 offset:2048
	ds_read_b128 v[176:179], v163 offset:3072
	s_add_u32 s24, s28, 0xb0000
	s_addc_u32 s25, s29, 0
	s_mov_b32 m0, s37
	v_lshl_add_u64 v[230:231], s[24:25], 0, v[134:135]
	ds_read_b128 v[180:183], v162 offset:32768
	ds_read_b128 v[184:187], v162 offset:33792
	ds_read_b128 v[206:209], v162 offset:34816
	ds_read_b128 v[210:213], v162 offset:35840
	ds_read_b128 v[214:217], v162 offset:36864
	ds_read_b128 v[218:221], v162 offset:37888
	ds_read_b128 v[222:225], v162 offset:38912
	ds_read_b128 v[226:229], v162 offset:39936
	global_load_lds_dwordx4 v[230:231], off
	v_lshl_add_u64 v[230:231], s[24:25], 0, v[132:133]
	s_mov_b32 m0, s42
	s_nop 0
	global_load_lds_dwordx4 v[230:231], off
	s_waitcnt lgkmcnt(8)
	s_barrier
	s_waitcnt lgkmcnt(0)
	s_setprio 1
	v_mfma_f32_16x16x32_bf16 v[126:129], v[164:167], v[180:183], v[126:129]
	v_mfma_f32_16x16x32_bf16 v[122:125], v[172:175], v[180:183], v[122:125]
	v_mfma_f32_16x16x32_bf16 v[114:117], v[164:167], v[206:209], v[114:117]
	v_mfma_f32_16x16x32_bf16 v[106:109], v[172:175], v[206:209], v[106:109]
	v_mfma_f32_16x16x32_bf16 v[98:101], v[164:167], v[214:217], v[98:101]
	v_mfma_f32_16x16x32_bf16 v[90:93], v[172:175], v[214:217], v[90:93]
	v_mfma_f32_16x16x32_bf16 v[82:85], v[164:167], v[222:225], v[82:85]
	v_mfma_f32_16x16x32_bf16 v[74:77], v[172:175], v[222:225], v[74:77]
	v_mfma_f32_16x16x32_bf16 v[126:129], v[168:171], v[184:187], v[126:129]
	v_mfma_f32_16x16x32_bf16 v[122:125], v[176:179], v[184:187], v[122:125]
	v_mfma_f32_16x16x32_bf16 v[114:117], v[168:171], v[210:213], v[114:117]
	v_mfma_f32_16x16x32_bf16 v[106:109], v[176:179], v[210:213], v[106:109]
	v_mfma_f32_16x16x32_bf16 v[98:101], v[168:171], v[218:221], v[98:101]
	v_mfma_f32_16x16x32_bf16 v[90:93], v[176:179], v[218:221], v[90:93]
	v_mfma_f32_16x16x32_bf16 v[82:85], v[168:171], v[226:229], v[82:85]
	v_mfma_f32_16x16x32_bf16 v[74:77], v[176:179], v[226:229], v[74:77]
	s_setprio 0
	s_barrier
	s_add_i32 s28, 0, 0x1c000
	s_add_i32 s24, s52, s31
	v_add_u32_e32 v163, s28, v144
	v_lshl_add_u64 v[140:141], v[140:141], 0, s[94:95]
	s_mov_b32 m0, s24
	ds_read_b128 v[230:233], v163
	ds_read_b128 v[234:237], v163 offset:1024
	ds_read_b128 v[238:241], v163 offset:2048
	ds_read_b128 v[242:245], v163 offset:3072
	global_load_lds_dwordx4 v[140:141], off
	v_lshl_add_u64 v[140:141], v[246:247], 0, s[94:95]
	s_add_i32 m0, s24, 0x2000
	s_nop 0
	global_load_lds_dwordx4 v[140:141], off
	s_barrier
	s_waitcnt lgkmcnt(0)
	s_setprio 1
	v_mfma_f32_16x16x32_bf16 v[118:121], v[230:233], v[180:183], v[118:121]
	v_mfma_f32_16x16x32_bf16 v[110:113], v[238:241], v[180:183], v[110:113]
	v_mfma_f32_16x16x32_bf16 v[102:105], v[230:233], v[206:209], v[102:105]
	v_mfma_f32_16x16x32_bf16 v[94:97], v[238:241], v[206:209], v[94:97]
	v_mfma_f32_16x16x32_bf16 v[86:89], v[230:233], v[214:217], v[86:89]
	v_mfma_f32_16x16x32_bf16 v[78:81], v[238:241], v[214:217], v[78:81]
	v_mfma_f32_16x16x32_bf16 v[70:73], v[230:233], v[222:225], v[70:73]
	v_mfma_f32_16x16x32_bf16 v[66:69], v[238:241], v[222:225], v[66:69]
	v_mfma_f32_16x16x32_bf16 v[118:121], v[234:237], v[184:187], v[118:121]
	v_mfma_f32_16x16x32_bf16 v[110:113], v[242:245], v[184:187], v[110:113]
	v_mfma_f32_16x16x32_bf16 v[102:105], v[234:237], v[210:213], v[102:105]
	v_mfma_f32_16x16x32_bf16 v[94:97], v[242:245], v[210:213], v[94:97]
	v_mfma_f32_16x16x32_bf16 v[86:89], v[234:237], v[218:221], v[86:89]
	v_mfma_f32_16x16x32_bf16 v[78:81], v[242:245], v[218:221], v[78:81]
	v_mfma_f32_16x16x32_bf16 v[70:73], v[234:237], v[226:229], v[70:73]
	v_mfma_f32_16x16x32_bf16 v[66:69], v[242:245], v[226:229], v[66:69]
	s_setprio 0
	s_mov_b32 m0, s44
	v_lshl_add_u64 v[140:141], v[248:249], 0, s[94:95]
	s_barrier
	ds_read_b128 v[180:183], v162 offset:49152
	ds_read_b128 v[184:187], v162 offset:50176
	ds_read_b128 v[206:209], v162 offset:51200
	ds_read_b128 v[210:213], v162 offset:52224
	ds_read_b128 v[214:217], v162 offset:53248
	ds_read_b128 v[218:221], v162 offset:54272
	ds_read_b128 v[222:225], v162 offset:55296
	ds_read_b128 v[226:229], v162 offset:56320
	global_load_lds_dwordx4 v[140:141], off
	v_lshl_add_u64 v[140:141], v[250:251], 0, s[94:95]
	s_mov_b32 m0, s45
	s_nop 0
	global_load_lds_dwordx4 v[140:141], off
	s_barrier
	s_waitcnt lgkmcnt(0)
	s_setprio 1
	v_mfma_f32_16x16x32_bf16 v[62:65], v[164:167], v[180:183], v[62:65]
	v_mfma_f32_16x16x32_bf16 v[58:61], v[172:175], v[180:183], v[58:61]
	v_mfma_f32_16x16x32_bf16 v[50:53], v[164:167], v[206:209], v[50:53]
	v_mfma_f32_16x16x32_bf16 v[42:45], v[172:175], v[206:209], v[42:45]
	v_mfma_f32_16x16x32_bf16 v[34:37], v[164:167], v[214:217], v[34:37]
	v_mfma_f32_16x16x32_bf16 v[26:29], v[172:175], v[214:217], v[26:29]
	v_mfma_f32_16x16x32_bf16 v[18:21], v[164:167], v[222:225], v[18:21]
	v_mfma_f32_16x16x32_bf16 v[10:13], v[172:175], v[222:225], v[10:13]
	v_mfma_f32_16x16x32_bf16 v[62:65], v[168:171], v[184:187], v[62:65]
	v_mfma_f32_16x16x32_bf16 v[58:61], v[176:179], v[184:187], v[58:61]
	v_mfma_f32_16x16x32_bf16 v[50:53], v[168:171], v[210:213], v[50:53]
	v_mfma_f32_16x16x32_bf16 v[42:45], v[176:179], v[210:213], v[42:45]
	v_mfma_f32_16x16x32_bf16 v[34:37], v[168:171], v[218:221], v[34:37]
	v_mfma_f32_16x16x32_bf16 v[26:29], v[176:179], v[218:221], v[26:29]
	v_mfma_f32_16x16x32_bf16 v[18:21], v[168:171], v[226:229], v[18:21]
	v_mfma_f32_16x16x32_bf16 v[10:13], v[176:179], v[226:229], v[10:13]
	s_setprio 0
	s_barrier
	s_add_u32 s24, s26, 0xb0080
	s_addc_u32 s25, s27, 0
	s_add_i32 s26, s28, s31
	v_lshl_add_u64 v[140:141], s[24:25], 0, v[0:1]
	s_mov_b32 m0, s26
	s_nop 0
	global_load_lds_dwordx4 v[140:141], off
	v_lshl_add_u64 v[140:141], s[24:25], 0, v[130:131]
	s_add_i32 m0, s26, 0x2000
	s_nop 0
	global_load_lds_dwordx4 v[140:141], off
	s_waitcnt vmcnt(6)
	s_barrier
	s_setprio 1
	v_mfma_f32_16x16x32_bf16 v[54:57], v[230:233], v[180:183], v[54:57]
	v_mfma_f32_16x16x32_bf16 v[46:49], v[238:241], v[180:183], v[46:49]
	v_mfma_f32_16x16x32_bf16 v[38:41], v[230:233], v[206:209], v[38:41]
	v_mfma_f32_16x16x32_bf16 v[30:33], v[238:241], v[206:209], v[30:33]
	v_mfma_f32_16x16x32_bf16 v[22:25], v[230:233], v[214:217], v[22:25]
	v_mfma_f32_16x16x32_bf16 v[14:17], v[238:241], v[214:217], v[14:17]
	v_mfma_f32_16x16x32_bf16 v[6:9], v[230:233], v[222:225], v[6:9]
	v_mfma_f32_16x16x32_bf16 v[2:5], v[238:241], v[222:225], v[2:5]
	v_mfma_f32_16x16x32_bf16 v[54:57], v[234:237], v[184:187], v[54:57]
	v_mfma_f32_16x16x32_bf16 v[46:49], v[242:245], v[184:187], v[46:49]
	v_mfma_f32_16x16x32_bf16 v[38:41], v[234:237], v[210:213], v[38:41]
	v_mfma_f32_16x16x32_bf16 v[30:33], v[242:245], v[210:213], v[30:33]
	v_mfma_f32_16x16x32_bf16 v[22:25], v[234:237], v[218:221], v[22:25]
	v_mfma_f32_16x16x32_bf16 v[14:17], v[242:245], v[218:221], v[14:17]
	v_mfma_f32_16x16x32_bf16 v[6:9], v[234:237], v[226:229], v[6:9]
	v_mfma_f32_16x16x32_bf16 v[2:5], v[242:245], v[226:229], v[2:5]
	s_setprio 0
	s_add_i32 s51, s51, 2
	s_add_u32 s40, s40, 0x100
	s_addc_u32 s41, s41, 0
	s_cmp_gt_u32 s51, 41
	s_mov_b64 s[24:25], s[22:23]
	s_barrier
	s_cbranch_scc0 .LBB0_331
	v_lshl_or_b32 v140, s50, 8, v145
	v_lshl_add_u32 v164, s49, 8, v143
	v_ashrrev_i32_e32 v141, 31, v140
	v_ashrrev_i32_e32 v165, 31, v164
	v_lshl_add_u64 v[166:167], v[140:141], 1, s[20:21]
	v_lshlrev_b64 v[140:141], 11, v[164:165]
	v_lshl_add_u64 v[140:141], v[166:167], 0, v[140:141]
	v_pk_add_f32 v[128:129], v[128:129], 0 op_sel_hi:[1,0]
	v_pk_add_f32 v[126:127], v[126:127], 0 op_sel_hi:[1,0]
	v_pk_add_f32 v[168:169], v[124:125], 0 op_sel_hi:[1,0]
	v_pk_add_f32 v[124:125], v[122:123], 0 op_sel_hi:[1,0]
	v_cvt_pk_bf16_f32 v122, v126, v127
	v_cvt_pk_bf16_f32 v123, v128, v129
	v_pk_add_f32 v[118:119], v[118:119], 0 op_sel_hi:[1,0]
	v_cvt_pk_bf16_f32 v124, v124, v125
	v_cvt_pk_bf16_f32 v125, v168, v169
	global_store_dwordx4 v[140:141], v[122:125], off
	v_pk_add_f32 v[120:121], v[120:121], 0 op_sel_hi:[1,0]
	v_pk_add_f32 v[114:115], v[114:115], 0 op_sel_hi:[1,0]
	v_pk_add_f32 v[122:123], v[112:113], 0 op_sel_hi:[1,0]
	v_pk_add_f32 v[112:113], v[110:111], 0 op_sel_hi:[1,0]
	v_cvt_pk_bf16_f32 v110, v118, v119
	v_cvt_pk_bf16_f32 v111, v120, v121
	v_pk_add_f32 v[102:103], v[102:103], 0 op_sel_hi:[1,0]
	v_cvt_pk_bf16_f32 v112, v112, v113
	v_cvt_pk_bf16_f32 v113, v122, v123
	global_store_dwordx4 v[140:141], v[110:113], off offset:256
	v_pk_add_f32 v[104:105], v[104:105], 0 op_sel_hi:[1,0]
	v_pk_add_f32 v[98:99], v[98:99], 0 op_sel_hi:[1,0]
	v_or_b32_e32 v110, 16, v164
	v_ashrrev_i32_e32 v111, 31, v110
	v_lshlrev_b64 v[110:111], 11, v[110:111]
	v_lshl_add_u64 v[110:111], v[166:167], 0, v[110:111]
	v_pk_add_f32 v[112:113], v[116:117], 0 op_sel_hi:[1,0]
	v_pk_add_f32 v[116:117], v[108:109], 0 op_sel_hi:[1,0]
	v_pk_add_f32 v[108:109], v[106:107], 0 op_sel_hi:[1,0]
	v_cvt_pk_bf16_f32 v106, v114, v115
	v_cvt_pk_bf16_f32 v107, v112, v113
	v_pk_add_f32 v[86:87], v[86:87], 0 op_sel_hi:[1,0]
	v_cvt_pk_bf16_f32 v108, v108, v109
	v_cvt_pk_bf16_f32 v109, v116, v117
	global_store_dwordx4 v[110:111], v[106:109], off
	v_pk_add_f32 v[88:89], v[88:89], 0 op_sel_hi:[1,0]
	v_pk_add_f32 v[82:83], v[82:83], 0 op_sel_hi:[1,0]
	v_pk_add_f32 v[106:107], v[96:97], 0 op_sel_hi:[1,0]
	v_pk_add_f32 v[96:97], v[94:95], 0 op_sel_hi:[1,0]
	v_cvt_pk_bf16_f32 v94, v102, v103
	v_cvt_pk_bf16_f32 v95, v104, v105
	v_pk_add_f32 v[72:73], v[72:73], 0 op_sel_hi:[1,0]
	v_cvt_pk_bf16_f32 v96, v96, v97
	v_cvt_pk_bf16_f32 v97, v106, v107
	global_store_dwordx4 v[110:111], v[94:97], off offset:256
	v_pk_add_f32 v[70:71], v[70:71], 0 op_sel_hi:[1,0]
	v_pk_add_f32 v[62:63], v[62:63], 0 op_sel_hi:[1,0]
	v_or_b32_e32 v94, 32, v164
	v_ashrrev_i32_e32 v95, 31, v94
	v_lshlrev_b64 v[94:95], 11, v[94:95]
	v_lshl_add_u64 v[94:95], v[166:167], 0, v[94:95]
	v_pk_add_f32 v[96:97], v[100:101], 0 op_sel_hi:[1,0]
	v_pk_add_f32 v[100:101], v[92:93], 0 op_sel_hi:[1,0]
	v_pk_add_f32 v[92:93], v[90:91], 0 op_sel_hi:[1,0]
	v_cvt_pk_bf16_f32 v90, v98, v99
	v_cvt_pk_bf16_f32 v91, v96, v97
	v_pk_add_f32 v[64:65], v[64:65], 0 op_sel_hi:[1,0]
	v_cvt_pk_bf16_f32 v92, v92, v93
	v_cvt_pk_bf16_f32 v93, v100, v101
	global_store_dwordx4 v[94:95], v[90:93], off
	s_mov_b64 s[22:23], 0x40000
	v_pk_add_f32 v[56:57], v[56:57], 0 op_sel_hi:[1,0]
	v_pk_add_f32 v[90:91], v[80:81], 0 op_sel_hi:[1,0]
	v_pk_add_f32 v[80:81], v[78:79], 0 op_sel_hi:[1,0]
	v_cvt_pk_bf16_f32 v78, v86, v87
	v_cvt_pk_bf16_f32 v79, v88, v89
	v_pk_add_f32 v[54:55], v[54:55], 0 op_sel_hi:[1,0]
	v_cvt_pk_bf16_f32 v80, v80, v81
	v_cvt_pk_bf16_f32 v81, v90, v91
	global_store_dwordx4 v[94:95], v[78:81], off offset:256
	v_pk_add_f32 v[50:51], v[50:51], 0 op_sel_hi:[1,0]
	v_pk_add_f32 v[40:41], v[40:41], 0 op_sel_hi:[1,0]
	v_or_b32_e32 v78, 48, v164
	v_ashrrev_i32_e32 v79, 31, v78
	v_lshlrev_b64 v[78:79], 11, v[78:79]
	v_lshl_add_u64 v[78:79], v[166:167], 0, v[78:79]
	v_pk_add_f32 v[80:81], v[84:85], 0 op_sel_hi:[1,0]
	v_pk_add_f32 v[84:85], v[76:77], 0 op_sel_hi:[1,0]
	v_pk_add_f32 v[76:77], v[74:75], 0 op_sel_hi:[1,0]
	v_cvt_pk_bf16_f32 v74, v82, v83
	v_cvt_pk_bf16_f32 v75, v80, v81
	v_pk_add_f32 v[38:39], v[38:39], 0 op_sel_hi:[1,0]
	v_cvt_pk_bf16_f32 v76, v76, v77
	v_cvt_pk_bf16_f32 v77, v84, v85
	global_store_dwordx4 v[78:79], v[74:77], off
	v_pk_add_f32 v[34:35], v[34:35], 0 op_sel_hi:[1,0]
	v_pk_add_f32 v[24:25], v[24:25], 0 op_sel_hi:[1,0]
	v_pk_add_f32 v[74:75], v[68:69], 0 op_sel_hi:[1,0]
	v_pk_add_f32 v[68:69], v[66:67], 0 op_sel_hi:[1,0]
	v_cvt_pk_bf16_f32 v66, v70, v71
	v_cvt_pk_bf16_f32 v67, v72, v73
	v_pk_add_f32 v[22:23], v[22:23], 0 op_sel_hi:[1,0]
	v_cvt_pk_bf16_f32 v68, v68, v69
	v_cvt_pk_bf16_f32 v69, v74, v75
	global_store_dwordx4 v[78:79], v[66:69], off offset:256
	v_pk_add_f32 v[18:19], v[18:19], 0 op_sel_hi:[1,0]
	s_mov_b32 s50, s47
	v_pk_add_f32 v[68:69], v[60:61], 0 op_sel_hi:[1,0]
	v_pk_add_f32 v[60:61], v[58:59], 0 op_sel_hi:[1,0]
	v_cvt_pk_bf16_f32 v58, v62, v63
	v_add_co_u32_e32 v62, vcc, s67, v140
	v_cvt_pk_bf16_f32 v59, v64, v65
	v_cvt_pk_bf16_f32 v60, v60, v61
	v_cvt_pk_bf16_f32 v61, v68, v69
	v_lshl_add_u64 v[66:67], v[140:141], 0, s[22:23]
	s_nop 0
	v_addc_co_u32_e32 v63, vcc, 0, v141, vcc
	global_store_dwordx4 v[62:63], v[58:61], off
	s_mov_b64 s[22:23], 0x48000
	s_mov_b32 s49, s48
	v_pk_add_f32 v[58:59], v[48:49], 0 op_sel_hi:[1,0]
	v_pk_add_f32 v[48:49], v[46:47], 0 op_sel_hi:[1,0]
	v_cvt_pk_bf16_f32 v46, v54, v55
	v_cvt_pk_bf16_f32 v47, v56, v57
	s_mov_b64 s[24:25], s[2:3]
	v_cvt_pk_bf16_f32 v48, v48, v49
	v_cvt_pk_bf16_f32 v49, v58, v59
	global_store_dwordx4 v[66:67], v[46:49], off offset:256
	v_pk_add_f32 v[8:9], v[8:9], 0 op_sel_hi:[1,0]
	v_pk_add_f32 v[6:7], v[6:7], 0 op_sel_hi:[1,0]
	v_pk_add_f32 v[48:49], v[52:53], 0 op_sel_hi:[1,0]
	v_pk_add_f32 v[52:53], v[44:45], 0 op_sel_hi:[1,0]
	v_pk_add_f32 v[44:45], v[42:43], 0 op_sel_hi:[1,0]
	v_cvt_pk_bf16_f32 v42, v50, v51
	v_cvt_pk_bf16_f32 v43, v48, v49
	v_add_co_u32_e32 v48, vcc, s68, v140
	v_cvt_pk_bf16_f32 v44, v44, v45
	v_cvt_pk_bf16_f32 v45, v52, v53
	v_lshl_add_u64 v[46:47], v[140:141], 0, s[22:23]
	s_nop 0
	v_addc_co_u32_e32 v49, vcc, 0, v141, vcc
	global_store_dwordx4 v[48:49], v[42:45], off
	s_mov_b64 s[22:23], 0x50000
	s_nop 0
	v_pk_add_f32 v[42:43], v[32:33], 0 op_sel_hi:[1,0]
	v_pk_add_f32 v[32:33], v[30:31], 0 op_sel_hi:[1,0]
	v_cvt_pk_bf16_f32 v30, v38, v39
	v_cvt_pk_bf16_f32 v31, v40, v41
	s_nop 0
	v_cvt_pk_bf16_f32 v32, v32, v33
	v_cvt_pk_bf16_f32 v33, v42, v43
	global_store_dwordx4 v[46:47], v[30:33], off offset:256
	s_nop 1
	v_lshl_add_u64 v[30:31], v[140:141], 0, s[22:23]
	v_pk_add_f32 v[32:33], v[36:37], 0 op_sel_hi:[1,0]
	s_mov_b32 s22, 0x50000
	v_pk_add_f32 v[36:37], v[28:29], 0 op_sel_hi:[1,0]
	v_pk_add_f32 v[28:29], v[26:27], 0 op_sel_hi:[1,0]
	v_cvt_pk_bf16_f32 v26, v34, v35
	v_cvt_pk_bf16_f32 v27, v32, v33
	v_add_co_u32_e32 v32, vcc, s22, v140
	v_cvt_pk_bf16_f32 v28, v28, v29
	v_cvt_pk_bf16_f32 v29, v36, v37
	s_mov_b64 s[22:23], 0x58000
	s_nop 0
	v_addc_co_u32_e32 v33, vcc, 0, v141, vcc
	global_store_dwordx4 v[32:33], v[26:29], off
	s_nop 1
	v_pk_add_f32 v[26:27], v[16:17], 0 op_sel_hi:[1,0]
	v_pk_add_f32 v[16:17], v[14:15], 0 op_sel_hi:[1,0]
	v_cvt_pk_bf16_f32 v14, v22, v23
	v_cvt_pk_bf16_f32 v15, v24, v25
	s_nop 0
	v_cvt_pk_bf16_f32 v16, v16, v17
	v_cvt_pk_bf16_f32 v17, v26, v27
	global_store_dwordx4 v[30:31], v[14:17], off offset:256
	s_nop 1
	v_lshl_add_u64 v[14:15], v[140:141], 0, s[22:23]
	v_pk_add_f32 v[16:17], v[20:21], 0 op_sel_hi:[1,0]
	s_mov_b32 s22, 0x58000
	v_pk_add_f32 v[20:21], v[12:13], 0 op_sel_hi:[1,0]
	v_pk_add_f32 v[12:13], v[10:11], 0 op_sel_hi:[1,0]
	v_cvt_pk_bf16_f32 v10, v18, v19
	v_cvt_pk_bf16_f32 v11, v16, v17
	v_add_co_u32_e32 v16, vcc, s22, v140
	v_cvt_pk_bf16_f32 v12, v12, v13
	v_cvt_pk_bf16_f32 v13, v20, v21
	s_mov_b64 s[22:23], s[0:1]
	s_nop 0
	v_addc_co_u32_e32 v17, vcc, 0, v141, vcc
	global_store_dwordx4 v[16:17], v[10:13], off
	s_and_b64 vcc, exec, s[38:39]
	s_nop 0
	v_pk_add_f32 v[10:11], v[4:5], 0 op_sel_hi:[1,0]
	v_pk_add_f32 v[4:5], v[2:3], 0 op_sel_hi:[1,0]
	v_cvt_pk_bf16_f32 v2, v6, v7
	v_cvt_pk_bf16_f32 v3, v8, v9
	s_nop 0
	v_cvt_pk_bf16_f32 v4, v4, v5
	v_cvt_pk_bf16_f32 v5, v10, v11
	global_store_dwordx4 v[14:15], v[2:5], off offset:256
	s_cbranch_vccz .LBB0_320
	s_waitcnt vmcnt(16)
	s_cmpk_gt_u32 s30, 0xff
	s_cbranch_scc1 .LBB0_335
	s_barrier

.LBB0_360:
	s_add_u32 s44, s42, 0xfffc0080
	s_addc_u32 s45, s43, -1
	s_add_i32 s63, 0, 0x10000
	v_add_u32_e32 v0, s63, v206
	ds_read_b128 v[82:85], v0
	ds_read_b128 v[86:89], v0 offset:1024
	ds_read_b128 v[90:93], v0 offset:2048
	ds_read_b128 v[94:97], v0 offset:3072
	s_cmp_eq_u32 s62, 12
	s_cselect_b32 s47, s1, s45
	s_cselect_b32 s46, s3, s44
	s_cselect_b32 s45, s31, s61
	s_cselect_b32 s44, s35, s60
	v_lshl_add_u64 v[230:231], s[42:43], 0, v[174:175]
	s_add_i32 m0, s51, 0xc000
	ds_read_b128 v[176:179], v208
	ds_read_b128 v[180:183], v208 offset:1024
	ds_read_b128 v[184:187], v208 offset:2048
	ds_read_b128 v[210:213], v208 offset:3072
	ds_read_b128 v[214:217], v208 offset:4096
	ds_read_b128 v[218:221], v208 offset:5120
	ds_read_b128 v[222:225], v208 offset:6144
	ds_read_b128 v[226:229], v208 offset:7168
	global_load_lds_dwordx4 v[230:231], off
	v_lshl_add_u64 v[230:231], s[42:43], 0, v[172:173]
	s_add_i32 m0, s51, 0xe000
	s_nop 0
	global_load_lds_dwordx4 v[230:231], off
	s_waitcnt lgkmcnt(8)
	s_barrier
	s_waitcnt lgkmcnt(0)
	s_setprio 1
	v_mfma_f32_16x16x32_bf16 v[142:145], v[82:85], v[176:179], v[142:145]
	v_mfma_f32_16x16x32_bf16 v[138:141], v[90:93], v[176:179], v[138:141]
	v_mfma_f32_16x16x32_bf16 v[126:129], v[82:85], v[184:187], v[126:129]
	v_mfma_f32_16x16x32_bf16 v[122:125], v[90:93], v[184:187], v[122:125]
	v_mfma_f32_16x16x32_bf16 v[110:113], v[82:85], v[214:217], v[110:113]
	v_mfma_f32_16x16x32_bf16 v[106:109], v[90:93], v[214:217], v[106:109]
	v_mfma_f32_16x16x32_bf16 v[78:81], v[82:85], v[222:225], v[78:81]
	v_mfma_f32_16x16x32_bf16 v[74:77], v[90:93], v[222:225], v[74:77]
	v_mfma_f32_16x16x32_bf16 v[142:145], v[86:89], v[180:183], v[142:145]
	v_mfma_f32_16x16x32_bf16 v[138:141], v[94:97], v[180:183], v[138:141]
	v_mfma_f32_16x16x32_bf16 v[126:129], v[86:89], v[210:213], v[126:129]
	v_mfma_f32_16x16x32_bf16 v[122:125], v[94:97], v[210:213], v[122:125]
	v_mfma_f32_16x16x32_bf16 v[110:113], v[86:89], v[218:221], v[110:113]
	v_mfma_f32_16x16x32_bf16 v[106:109], v[94:97], v[218:221], v[106:109]
	v_mfma_f32_16x16x32_bf16 v[78:81], v[86:89], v[226:229], v[78:81]
	v_mfma_f32_16x16x32_bf16 v[74:77], v[94:97], v[226:229], v[74:77]
	s_setprio 0
	s_barrier
	s_add_i32 s66, 0, 0x14000
	s_add_i32 s63, s63, s50
	v_add_u32_e32 v0, s66, v206
	v_lshl_add_u64 v[246:247], s[44:45], 0, v[164:165]
	s_mov_b32 m0, s63
	ds_read_b128 v[230:233], v0
	ds_read_b128 v[234:237], v0 offset:1024
	ds_read_b128 v[238:241], v0 offset:2048
	ds_read_b128 v[242:245], v0 offset:3072
	global_load_lds_dwordx4 v[246:247], off
	v_lshl_add_u64 v[248:249], s[44:45], 0, v[168:169]
	s_add_i32 m0, s63, 0x2000
	s_nop 0
	global_load_lds_dwordx4 v[248:249], off
	s_barrier
	s_waitcnt lgkmcnt(0)
	s_setprio 1
	v_mfma_f32_16x16x32_bf16 v[134:137], v[230:233], v[176:179], v[134:137]
	v_mfma_f32_16x16x32_bf16 v[130:133], v[238:241], v[176:179], v[130:133]
	v_mfma_f32_16x16x32_bf16 v[118:121], v[230:233], v[184:187], v[118:121]
	v_mfma_f32_16x16x32_bf16 v[114:117], v[238:241], v[184:187], v[114:117]
	v_mfma_f32_16x16x32_bf16 v[102:105], v[230:233], v[214:217], v[102:105]
	v_mfma_f32_16x16x32_bf16 v[98:101], v[238:241], v[214:217], v[98:101]
	v_mfma_f32_16x16x32_bf16 v[70:73], v[230:233], v[222:225], v[70:73]
	v_mfma_f32_16x16x32_bf16 v[66:69], v[238:241], v[222:225], v[66:69]
	v_mfma_f32_16x16x32_bf16 v[134:137], v[234:237], v[180:183], v[134:137]
	v_mfma_f32_16x16x32_bf16 v[130:133], v[242:245], v[180:183], v[130:133]
	v_mfma_f32_16x16x32_bf16 v[118:121], v[234:237], v[210:213], v[118:121]
	v_mfma_f32_16x16x32_bf16 v[114:117], v[242:245], v[210:213], v[114:117]
	v_mfma_f32_16x16x32_bf16 v[102:105], v[234:237], v[218:221], v[102:105]
	v_mfma_f32_16x16x32_bf16 v[98:101], v[242:245], v[218:221], v[98:101]
	v_mfma_f32_16x16x32_bf16 v[70:73], v[234:237], v[226:229], v[70:73]
	v_mfma_f32_16x16x32_bf16 v[66:69], v[242:245], v[226:229], v[66:69]
	s_setprio 0
	s_mov_b32 m0, s51
	v_lshl_add_u64 v[250:251], s[46:47], 0, v[162:163]
	s_barrier
	ds_read_b128 v[176:179], v208 offset:16384
	ds_read_b128 v[180:183], v208 offset:17408
	ds_read_b128 v[184:187], v208 offset:18432
	ds_read_b128 v[210:213], v208 offset:19456
	ds_read_b128 v[214:217], v208 offset:20480
	ds_read_b128 v[218:221], v208 offset:21504
	ds_read_b128 v[222:225], v208 offset:22528
	ds_read_b128 v[226:229], v208 offset:23552
	global_load_lds_dwordx4 v[250:251], off
	v_lshl_add_u64 v[252:253], s[46:47], 0, v[166:167]
	s_mov_b32 m0, s52
	s_nop 0
	global_load_lds_dwordx4 v[252:253], off
	s_barrier
	s_waitcnt lgkmcnt(0)
	s_setprio 1
	v_mfma_f32_16x16x32_bf16 v[62:65], v[82:85], v[176:179], v[62:65]
	v_mfma_f32_16x16x32_bf16 v[58:61], v[90:93], v[176:179], v[58:61]
	v_mfma_f32_16x16x32_bf16 v[46:49], v[82:85], v[184:187], v[46:49]
	v_mfma_f32_16x16x32_bf16 v[42:45], v[90:93], v[184:187], v[42:45]
	v_mfma_f32_16x16x32_bf16 v[30:33], v[82:85], v[214:217], v[30:33]
	v_mfma_f32_16x16x32_bf16 v[26:29], v[90:93], v[214:217], v[26:29]
	v_mfma_f32_16x16x32_bf16 v[14:17], v[82:85], v[222:225], v[14:17]
	v_mfma_f32_16x16x32_bf16 v[10:13], v[90:93], v[222:225], v[10:13]
	v_mfma_f32_16x16x32_bf16 v[62:65], v[86:89], v[180:183], v[62:65]
	v_mfma_f32_16x16x32_bf16 v[58:61], v[94:97], v[180:183], v[58:61]
	v_mfma_f32_16x16x32_bf16 v[46:49], v[86:89], v[210:213], v[46:49]
	v_mfma_f32_16x16x32_bf16 v[42:45], v[94:97], v[210:213], v[42:45]
	v_mfma_f32_16x16x32_bf16 v[30:33], v[86:89], v[218:221], v[30:33]
	v_mfma_f32_16x16x32_bf16 v[26:29], v[94:97], v[218:221], v[26:29]
	v_mfma_f32_16x16x32_bf16 v[14:17], v[86:89], v[226:229], v[14:17]
	v_mfma_f32_16x16x32_bf16 v[10:13], v[94:97], v[226:229], v[10:13]
	s_setprio 0
	s_barrier
	s_add_u32 s64, s44, 0x40000
	s_addc_u32 s65, s45, 0
	s_add_i32 s63, s66, s50
	v_lshl_add_u64 v[82:83], s[64:65], 0, v[164:165]
	s_mov_b32 m0, s63
	s_nop 0
	global_load_lds_dwordx4 v[82:83], off
	v_lshl_add_u64 v[82:83], s[64:65], 0, v[168:169]
	s_add_i32 m0, s63, 0x2000
	s_nop 0
	global_load_lds_dwordx4 v[82:83], off
	s_waitcnt vmcnt(6)
	s_barrier
	s_setprio 1
	v_mfma_f32_16x16x32_bf16 v[54:57], v[230:233], v[176:179], v[54:57]
	v_mfma_f32_16x16x32_bf16 v[50:53], v[238:241], v[176:179], v[50:53]
	v_mfma_f32_16x16x32_bf16 v[38:41], v[230:233], v[184:187], v[38:41]
	v_mfma_f32_16x16x32_bf16 v[34:37], v[238:241], v[184:187], v[34:37]
	v_mfma_f32_16x16x32_bf16 v[22:25], v[230:233], v[214:217], v[22:25]
	v_mfma_f32_16x16x32_bf16 v[18:21], v[238:241], v[214:217], v[18:21]
	v_mfma_f32_16x16x32_bf16 v[6:9], v[230:233], v[222:225], v[6:9]
	v_mfma_f32_16x16x32_bf16 v[2:5], v[238:241], v[222:225], v[2:5]
	v_mfma_f32_16x16x32_bf16 v[54:57], v[234:237], v[180:183], v[54:57]
	v_mfma_f32_16x16x32_bf16 v[50:53], v[242:245], v[180:183], v[50:53]
	v_mfma_f32_16x16x32_bf16 v[38:41], v[234:237], v[210:213], v[38:41]
	v_mfma_f32_16x16x32_bf16 v[34:37], v[242:245], v[210:213], v[34:37]
	v_mfma_f32_16x16x32_bf16 v[22:25], v[234:237], v[218:221], v[22:25]
	v_mfma_f32_16x16x32_bf16 v[18:21], v[242:245], v[218:221], v[18:21]
	v_mfma_f32_16x16x32_bf16 v[6:9], v[234:237], v[226:229], v[6:9]
	v_mfma_f32_16x16x32_bf16 v[2:5], v[242:245], v[226:229], v[2:5]
	s_setprio 0
	s_add_i32 s63, 0, 0x18000
	v_add_u32_e32 v0, s63, v206
	s_barrier
	ds_read_b128 v[82:85], v0
	ds_read_b128 v[86:89], v0 offset:1024
	ds_read_b128 v[90:93], v0 offset:2048
	ds_read_b128 v[94:97], v0 offset:3072
	s_add_u32 s46, s46, 0x40000
	s_addc_u32 s47, s47, 0
	s_mov_b32 m0, s53
	v_lshl_add_u64 v[230:231], s[46:47], 0, v[162:163]
	ds_read_b128 v[176:179], v208 offset:32768
	ds_read_b128 v[180:183], v208 offset:33792
	ds_read_b128 v[184:187], v208 offset:34816
	ds_read_b128 v[210:213], v208 offset:35840
	ds_read_b128 v[214:217], v208 offset:36864
	ds_read_b128 v[218:221], v208 offset:37888
	ds_read_b128 v[222:225], v208 offset:38912
	ds_read_b128 v[226:229], v208 offset:39936
	global_load_lds_dwordx4 v[230:231], off
	v_lshl_add_u64 v[230:231], s[46:47], 0, v[166:167]
	s_mov_b32 m0, s54
	s_nop 0
	global_load_lds_dwordx4 v[230:231], off
	s_waitcnt lgkmcnt(8)
	s_barrier
	s_waitcnt lgkmcnt(0)
	s_setprio 1
	v_mfma_f32_16x16x32_bf16 v[142:145], v[82:85], v[176:179], v[142:145]
	v_mfma_f32_16x16x32_bf16 v[138:141], v[90:93], v[176:179], v[138:141]
	v_mfma_f32_16x16x32_bf16 v[126:129], v[82:85], v[184:187], v[126:129]
	v_mfma_f32_16x16x32_bf16 v[122:125], v[90:93], v[184:187], v[122:125]
	v_mfma_f32_16x16x32_bf16 v[110:113], v[82:85], v[214:217], v[110:113]
	v_mfma_f32_16x16x32_bf16 v[106:109], v[90:93], v[214:217], v[106:109]
	v_mfma_f32_16x16x32_bf16 v[78:81], v[82:85], v[222:225], v[78:81]
	v_mfma_f32_16x16x32_bf16 v[74:77], v[90:93], v[222:225], v[74:77]
	v_mfma_f32_16x16x32_bf16 v[142:145], v[86:89], v[180:183], v[142:145]
	v_mfma_f32_16x16x32_bf16 v[138:141], v[94:97], v[180:183], v[138:141]
	v_mfma_f32_16x16x32_bf16 v[126:129], v[86:89], v[210:213], v[126:129]
	v_mfma_f32_16x16x32_bf16 v[122:125], v[94:97], v[210:213], v[122:125]
	v_mfma_f32_16x16x32_bf16 v[110:113], v[86:89], v[218:221], v[110:113]
	v_mfma_f32_16x16x32_bf16 v[106:109], v[94:97], v[218:221], v[106:109]
	v_mfma_f32_16x16x32_bf16 v[78:81], v[86:89], v[226:229], v[78:81]
	v_mfma_f32_16x16x32_bf16 v[74:77], v[94:97], v[226:229], v[74:77]
	s_setprio 0
	s_barrier
	s_add_i32 s46, 0, 0x1c000
	s_add_i32 s47, s63, s50
	v_add_u32_e32 v0, s46, v206
	v_lshl_add_u64 v[246:247], v[246:247], 0, s[94:95]
	s_mov_b32 m0, s47
	ds_read_b128 v[230:233], v0
	ds_read_b128 v[234:237], v0 offset:1024
	ds_read_b128 v[238:241], v0 offset:2048
	ds_read_b128 v[242:245], v0 offset:3072
	global_load_lds_dwordx4 v[246:247], off
	v_lshl_add_u64 v[246:247], v[248:249], 0, s[94:95]
	s_add_i32 m0, s47, 0x2000
	s_nop 0
	global_load_lds_dwordx4 v[246:247], off
	s_barrier
	s_waitcnt lgkmcnt(0)
	s_setprio 1
	v_mfma_f32_16x16x32_bf16 v[134:137], v[230:233], v[176:179], v[134:137]
	v_mfma_f32_16x16x32_bf16 v[130:133], v[238:241], v[176:179], v[130:133]
	v_mfma_f32_16x16x32_bf16 v[118:121], v[230:233], v[184:187], v[118:121]
	v_mfma_f32_16x16x32_bf16 v[114:117], v[238:241], v[184:187], v[114:117]
	v_mfma_f32_16x16x32_bf16 v[102:105], v[230:233], v[214:217], v[102:105]
	v_mfma_f32_16x16x32_bf16 v[98:101], v[238:241], v[214:217], v[98:101]
	v_mfma_f32_16x16x32_bf16 v[70:73], v[230:233], v[222:225], v[70:73]
	v_mfma_f32_16x16x32_bf16 v[66:69], v[238:241], v[222:225], v[66:69]
	v_mfma_f32_16x16x32_bf16 v[134:137], v[234:237], v[180:183], v[134:137]
	v_mfma_f32_16x16x32_bf16 v[130:133], v[242:245], v[180:183], v[130:133]
	v_mfma_f32_16x16x32_bf16 v[118:121], v[234:237], v[210:213], v[118:121]
	v_mfma_f32_16x16x32_bf16 v[114:117], v[242:245], v[210:213], v[114:117]
	v_mfma_f32_16x16x32_bf16 v[102:105], v[234:237], v[218:221], v[102:105]
	v_mfma_f32_16x16x32_bf16 v[98:101], v[242:245], v[218:221], v[98:101]
	v_mfma_f32_16x16x32_bf16 v[70:73], v[234:237], v[226:229], v[70:73]
	v_mfma_f32_16x16x32_bf16 v[66:69], v[242:245], v[226:229], v[66:69]
	s_setprio 0
	s_mov_b32 m0, s56
	v_lshl_add_u64 v[246:247], v[250:251], 0, s[94:95]
	s_barrier
	ds_read_b128 v[176:179], v208 offset:49152
	ds_read_b128 v[180:183], v208 offset:50176
	ds_read_b128 v[184:187], v208 offset:51200
	ds_read_b128 v[210:213], v208 offset:52224
	ds_read_b128 v[214:217], v208 offset:53248
	ds_read_b128 v[218:221], v208 offset:54272
	ds_read_b128 v[222:225], v208 offset:55296
	ds_read_b128 v[226:229], v208 offset:56320
	global_load_lds_dwordx4 v[246:247], off
	v_lshl_add_u64 v[246:247], v[252:253], 0, s[94:95]
	s_mov_b32 m0, s57
	s_nop 0
	global_load_lds_dwordx4 v[246:247], off
	s_barrier
	s_waitcnt lgkmcnt(0)
	s_setprio 1
	v_mfma_f32_16x16x32_bf16 v[62:65], v[82:85], v[176:179], v[62:65]
	v_mfma_f32_16x16x32_bf16 v[58:61], v[90:93], v[176:179], v[58:61]
	v_mfma_f32_16x16x32_bf16 v[46:49], v[82:85], v[184:187], v[46:49]
	v_mfma_f32_16x16x32_bf16 v[42:45], v[90:93], v[184:187], v[42:45]
	v_mfma_f32_16x16x32_bf16 v[30:33], v[82:85], v[214:217], v[30:33]
	v_mfma_f32_16x16x32_bf16 v[26:29], v[90:93], v[214:217], v[26:29]
	v_mfma_f32_16x16x32_bf16 v[14:17], v[82:85], v[222:225], v[14:17]
	v_mfma_f32_16x16x32_bf16 v[10:13], v[90:93], v[222:225], v[10:13]
	v_mfma_f32_16x16x32_bf16 v[62:65], v[86:89], v[180:183], v[62:65]
	v_mfma_f32_16x16x32_bf16 v[58:61], v[94:97], v[180:183], v[58:61]
	v_mfma_f32_16x16x32_bf16 v[46:49], v[86:89], v[210:213], v[46:49]
	v_mfma_f32_16x16x32_bf16 v[42:45], v[94:97], v[210:213], v[42:45]
	v_mfma_f32_16x16x32_bf16 v[30:33], v[86:89], v[218:221], v[30:33]
	v_mfma_f32_16x16x32_bf16 v[26:29], v[94:97], v[218:221], v[26:29]
	v_mfma_f32_16x16x32_bf16 v[14:17], v[86:89], v[226:229], v[14:17]
	v_mfma_f32_16x16x32_bf16 v[10:13], v[94:97], v[226:229], v[10:13]
	s_setprio 0
	s_barrier
	s_add_u32 s44, s44, 0x40080
	s_addc_u32 s45, s45, 0
	s_add_i32 s46, s46, s50
	v_lshl_add_u64 v[82:83], s[44:45], 0, v[164:165]
	s_mov_b32 m0, s46
	s_nop 0
	global_load_lds_dwordx4 v[82:83], off
	v_lshl_add_u64 v[82:83], s[44:45], 0, v[168:169]
	s_add_i32 m0, s46, 0x2000
	s_nop 0
	global_load_lds_dwordx4 v[82:83], off
	s_waitcnt vmcnt(6)
	s_barrier
	s_setprio 1
	v_mfma_f32_16x16x32_bf16 v[54:57], v[230:233], v[176:179], v[54:57]
	v_mfma_f32_16x16x32_bf16 v[50:53], v[238:241], v[176:179], v[50:53]
	v_mfma_f32_16x16x32_bf16 v[38:41], v[230:233], v[184:187], v[38:41]
	v_mfma_f32_16x16x32_bf16 v[34:37], v[238:241], v[184:187], v[34:37]
	v_mfma_f32_16x16x32_bf16 v[22:25], v[230:233], v[214:217], v[22:25]
	v_mfma_f32_16x16x32_bf16 v[18:21], v[238:241], v[214:217], v[18:21]
	v_mfma_f32_16x16x32_bf16 v[6:9], v[230:233], v[222:225], v[6:9]
	v_mfma_f32_16x16x32_bf16 v[2:5], v[238:241], v[222:225], v[2:5]
	v_mfma_f32_16x16x32_bf16 v[54:57], v[234:237], v[180:183], v[54:57]
	v_mfma_f32_16x16x32_bf16 v[50:53], v[242:245], v[180:183], v[50:53]
	v_mfma_f32_16x16x32_bf16 v[38:41], v[234:237], v[210:213], v[38:41]
	v_mfma_f32_16x16x32_bf16 v[34:37], v[242:245], v[210:213], v[34:37]
	v_mfma_f32_16x16x32_bf16 v[22:25], v[234:237], v[218:221], v[22:25]
	v_mfma_f32_16x16x32_bf16 v[18:21], v[242:245], v[218:221], v[18:21]
	v_mfma_f32_16x16x32_bf16 v[6:9], v[234:237], v[226:229], v[6:9]
	v_mfma_f32_16x16x32_bf16 v[2:5], v[242:245], v[226:229], v[2:5]
	s_setprio 0
	s_add_i32 s62, s62, 2
	s_add_u32 s60, s60, 0x100
	s_addc_u32 s61, s61, 0
	s_add_u32 s42, s42, 0x100
	s_addc_u32 s43, s43, 0
	s_cmp_gt_u32 s62, 13
	s_barrier
	s_cbranch_scc0 .LBB0_360
	v_lshl_or_b32 v180, s0, 8, v207
	v_ashrrev_i32_e32 v181, 31, v180
	v_mov_b32_e32 v86, 0
	v_cndmask_b32_e64 v0, 0, 1, s[26:27]
	v_lshl_add_u64 v[176:177], v[180:181], 2, s[22:23]
	v_cmp_ne_u32_e64 s[0:1], 1, v0
	s_andn2_b64 vcc, exec, s[26:27]
	v_mov_b32_e32 v94, 0
	v_mov_b32_e32 v95, v86
	v_mov_b32_e32 v96, 0
	v_mov_b32_e32 v97, 0
	s_cbranch_vccnz .LBB0_363
	global_load_dwordx4 v[94:97], v[176:177], off

.LBB0_586:
	s_add_u32 s22, s20, 0xfffc0080
	s_addc_u32 s23, s21, -1
	s_add_i32 s48, 0, 0x10000
	v_add_u32_e32 v140, s48, v143
	ds_read_b128 v[162:165], v140
	ds_read_b128 v[166:169], v140 offset:1024
	ds_read_b128 v[170:173], v140 offset:2048
	ds_read_b128 v[174:177], v140 offset:3072
	s_cmp_eq_u32 s47, 12
	s_cselect_b32 s25, s9, s23
	s_cselect_b32 s24, s43, s22
	s_cselect_b32 s23, s1, s46
	s_cselect_b32 s22, s44, s45
	v_lshl_add_u64 v[140:141], s[20:21], 0, v[136:137]
	s_add_i32 m0, s3, 0xc000
	ds_read_b128 v[178:181], v145
	ds_read_b128 v[182:185], v145 offset:1024
	ds_read_b128 v[206:209], v145 offset:2048
	ds_read_b128 v[210:213], v145 offset:3072
	ds_read_b128 v[214:217], v145 offset:4096
	ds_read_b128 v[218:221], v145 offset:5120
	ds_read_b128 v[222:225], v145 offset:6144
	ds_read_b128 v[226:229], v145 offset:7168
	global_load_lds_dwordx4 v[140:141], off
	v_lshl_add_u64 v[140:141], s[20:21], 0, v[138:139]
	s_add_i32 m0, s3, 0xe000
	s_nop 0
	global_load_lds_dwordx4 v[140:141], off
	s_waitcnt lgkmcnt(8)
	s_barrier
	s_waitcnt lgkmcnt(0)
	s_setprio 1
	v_mfma_f32_16x16x32_bf16 v[122:125], v[162:165], v[178:181], v[122:125]
	v_mfma_f32_16x16x32_bf16 v[114:117], v[170:173], v[178:181], v[114:117]
	v_mfma_f32_16x16x32_bf16 v[106:109], v[162:165], v[206:209], v[106:109]
	v_mfma_f32_16x16x32_bf16 v[98:101], v[170:173], v[206:209], v[98:101]
	v_mfma_f32_16x16x32_bf16 v[90:93], v[162:165], v[214:217], v[90:93]
	v_mfma_f32_16x16x32_bf16 v[82:85], v[170:173], v[214:217], v[82:85]
	v_mfma_f32_16x16x32_bf16 v[74:77], v[162:165], v[222:225], v[74:77]
	v_mfma_f32_16x16x32_bf16 v[66:69], v[170:173], v[222:225], v[66:69]
	v_mfma_f32_16x16x32_bf16 v[122:125], v[166:169], v[182:185], v[122:125]
	v_mfma_f32_16x16x32_bf16 v[114:117], v[174:177], v[182:185], v[114:117]
	v_mfma_f32_16x16x32_bf16 v[106:109], v[166:169], v[210:213], v[106:109]
	v_mfma_f32_16x16x32_bf16 v[98:101], v[174:177], v[210:213], v[98:101]
	v_mfma_f32_16x16x32_bf16 v[90:93], v[166:169], v[218:221], v[90:93]
	v_mfma_f32_16x16x32_bf16 v[82:85], v[174:177], v[218:221], v[82:85]
	v_mfma_f32_16x16x32_bf16 v[74:77], v[166:169], v[226:229], v[74:77]
	v_mfma_f32_16x16x32_bf16 v[66:69], v[174:177], v[226:229], v[66:69]
	s_setprio 0
	s_barrier
	s_add_i32 s50, 0, 0x14000
	v_add_u32_e32 v140, s50, v143
	s_add_i32 s48, s48, s29
	ds_read_b128 v[230:233], v140
	ds_read_b128 v[234:237], v140 offset:1024
	ds_read_b128 v[238:241], v140 offset:2048
	ds_read_b128 v[242:245], v140 offset:3072
	v_lshl_add_u64 v[140:141], s[22:23], 0, v[0:1]
	s_mov_b32 m0, s48
	v_lshl_add_u64 v[186:187], s[22:23], 0, v[130:131]
	global_load_lds_dwordx4 v[140:141], off
	s_add_i32 m0, s48, 0x2000
	s_nop 0
	global_load_lds_dwordx4 v[186:187], off
	s_barrier
	s_waitcnt lgkmcnt(0)
	s_setprio 1
	v_mfma_f32_16x16x32_bf16 v[126:129], v[230:233], v[178:181], v[126:129]
	v_mfma_f32_16x16x32_bf16 v[118:121], v[238:241], v[178:181], v[118:121]
	v_mfma_f32_16x16x32_bf16 v[110:113], v[230:233], v[206:209], v[110:113]
	v_mfma_f32_16x16x32_bf16 v[102:105], v[238:241], v[206:209], v[102:105]
	v_mfma_f32_16x16x32_bf16 v[94:97], v[230:233], v[214:217], v[94:97]
	v_mfma_f32_16x16x32_bf16 v[86:89], v[238:241], v[214:217], v[86:89]
	v_mfma_f32_16x16x32_bf16 v[78:81], v[230:233], v[222:225], v[78:81]
	v_mfma_f32_16x16x32_bf16 v[70:73], v[238:241], v[222:225], v[70:73]
	v_mfma_f32_16x16x32_bf16 v[126:129], v[234:237], v[182:185], v[126:129]
	v_mfma_f32_16x16x32_bf16 v[118:121], v[242:245], v[182:185], v[118:121]
	v_mfma_f32_16x16x32_bf16 v[110:113], v[234:237], v[210:213], v[110:113]
	v_mfma_f32_16x16x32_bf16 v[102:105], v[242:245], v[210:213], v[102:105]
	v_mfma_f32_16x16x32_bf16 v[94:97], v[234:237], v[218:221], v[94:97]
	v_mfma_f32_16x16x32_bf16 v[86:89], v[242:245], v[218:221], v[86:89]
	v_mfma_f32_16x16x32_bf16 v[78:81], v[234:237], v[226:229], v[78:81]
	v_mfma_f32_16x16x32_bf16 v[70:73], v[242:245], v[226:229], v[70:73]
	s_setprio 0
	s_mov_b32 m0, s3
	v_lshl_add_u64 v[246:247], s[24:25], 0, v[134:135]
	s_barrier
	ds_read_b128 v[178:181], v145 offset:16384
	ds_read_b128 v[182:185], v145 offset:17408
	ds_read_b128 v[206:209], v145 offset:18432
	ds_read_b128 v[210:213], v145 offset:19456
	ds_read_b128 v[214:217], v145 offset:20480
	ds_read_b128 v[218:221], v145 offset:21504
	ds_read_b128 v[222:225], v145 offset:22528
	ds_read_b128 v[226:229], v145 offset:23552
	global_load_lds_dwordx4 v[246:247], off
	v_lshl_add_u64 v[248:249], s[24:25], 0, v[132:133]
	s_mov_b32 m0, s31
	s_nop 0
	global_load_lds_dwordx4 v[248:249], off
	s_barrier
	s_waitcnt lgkmcnt(0)
	s_setprio 1
	v_mfma_f32_16x16x32_bf16 v[58:61], v[162:165], v[178:181], v[58:61]
	v_mfma_f32_16x16x32_bf16 v[50:53], v[170:173], v[178:181], v[50:53]
	v_mfma_f32_16x16x32_bf16 v[42:45], v[162:165], v[206:209], v[42:45]
	v_mfma_f32_16x16x32_bf16 v[34:37], v[170:173], v[206:209], v[34:37]
	v_mfma_f32_16x16x32_bf16 v[26:29], v[162:165], v[214:217], v[26:29]
	v_mfma_f32_16x16x32_bf16 v[18:21], v[170:173], v[214:217], v[18:21]
	v_mfma_f32_16x16x32_bf16 v[10:13], v[162:165], v[222:225], v[10:13]
	v_mfma_f32_16x16x32_bf16 v[6:9], v[170:173], v[222:225], v[6:9]
	v_mfma_f32_16x16x32_bf16 v[58:61], v[166:169], v[182:185], v[58:61]
	v_mfma_f32_16x16x32_bf16 v[50:53], v[174:177], v[182:185], v[50:53]
	v_mfma_f32_16x16x32_bf16 v[42:45], v[166:169], v[210:213], v[42:45]
	v_mfma_f32_16x16x32_bf16 v[34:37], v[174:177], v[210:213], v[34:37]
	v_mfma_f32_16x16x32_bf16 v[26:29], v[166:169], v[218:221], v[26:29]
	v_mfma_f32_16x16x32_bf16 v[18:21], v[174:177], v[218:221], v[18:21]
	v_mfma_f32_16x16x32_bf16 v[10:13], v[166:169], v[226:229], v[10:13]
	v_mfma_f32_16x16x32_bf16 v[6:9], v[174:177], v[226:229], v[6:9]
	s_setprio 0
	s_barrier
	s_add_u32 s48, s22, 0x40000
	s_addc_u32 s49, s23, 0
	s_add_i32 s50, s50, s29
	v_lshl_add_u64 v[162:163], s[48:49], 0, v[0:1]
	s_mov_b32 m0, s50
	s_nop 0
	global_load_lds_dwordx4 v[162:163], off
	v_lshl_add_u64 v[162:163], s[48:49], 0, v[130:131]
	s_add_i32 m0, s50, 0x2000
	s_nop 0
	global_load_lds_dwordx4 v[162:163], off
	s_waitcnt vmcnt(6)
	s_barrier
	s_setprio 1
	v_mfma_f32_16x16x32_bf16 v[62:65], v[230:233], v[178:181], v[62:65]
	v_mfma_f32_16x16x32_bf16 v[54:57], v[238:241], v[178:181], v[54:57]
	v_mfma_f32_16x16x32_bf16 v[46:49], v[230:233], v[206:209], v[46:49]
	v_mfma_f32_16x16x32_bf16 v[38:41], v[238:241], v[206:209], v[38:41]
	v_mfma_f32_16x16x32_bf16 v[30:33], v[230:233], v[214:217], v[30:33]
	v_mfma_f32_16x16x32_bf16 v[22:25], v[238:241], v[214:217], v[22:25]
	v_mfma_f32_16x16x32_bf16 v[14:17], v[230:233], v[222:225], v[14:17]
	v_mfma_f32_16x16x32_bf16 v[2:5], v[238:241], v[222:225], v[2:5]
	v_mfma_f32_16x16x32_bf16 v[62:65], v[234:237], v[182:185], v[62:65]
	v_mfma_f32_16x16x32_bf16 v[54:57], v[242:245], v[182:185], v[54:57]
	v_mfma_f32_16x16x32_bf16 v[46:49], v[234:237], v[210:213], v[46:49]
	v_mfma_f32_16x16x32_bf16 v[38:41], v[242:245], v[210:213], v[38:41]
	v_mfma_f32_16x16x32_bf16 v[30:33], v[234:237], v[218:221], v[30:33]
	v_mfma_f32_16x16x32_bf16 v[22:25], v[242:245], v[218:221], v[22:25]
	v_mfma_f32_16x16x32_bf16 v[14:17], v[234:237], v[226:229], v[14:17]
	v_mfma_f32_16x16x32_bf16 v[2:5], v[242:245], v[226:229], v[2:5]
	s_setprio 0
	s_add_i32 s48, 0, 0x18000
	v_add_u32_e32 v174, s48, v143
	s_barrier
	ds_read_b128 v[162:165], v174
	ds_read_b128 v[166:169], v174 offset:1024
	ds_read_b128 v[170:173], v174 offset:2048
	ds_read_b128 v[174:177], v174 offset:3072
	s_add_u32 s24, s24, 0x40000
	s_addc_u32 s25, s25, 0
	s_mov_b32 m0, s34
	v_lshl_add_u64 v[230:231], s[24:25], 0, v[134:135]
	ds_read_b128 v[178:181], v145 offset:32768
	ds_read_b128 v[182:185], v145 offset:33792
	ds_read_b128 v[206:209], v145 offset:34816
	ds_read_b128 v[210:213], v145 offset:35840
	ds_read_b128 v[214:217], v145 offset:36864
	ds_read_b128 v[218:221], v145 offset:37888
	ds_read_b128 v[222:225], v145 offset:38912
	ds_read_b128 v[226:229], v145 offset:39936
	global_load_lds_dwordx4 v[230:231], off
	v_lshl_add_u64 v[230:231], s[24:25], 0, v[132:133]
	s_mov_b32 m0, s35
	s_nop 0
	global_load_lds_dwordx4 v[230:231], off
	s_waitcnt lgkmcnt(8)
	s_barrier
	s_waitcnt lgkmcnt(0)
	s_setprio 1
	v_mfma_f32_16x16x32_bf16 v[122:125], v[162:165], v[178:181], v[122:125]
	v_mfma_f32_16x16x32_bf16 v[114:117], v[170:173], v[178:181], v[114:117]
	v_mfma_f32_16x16x32_bf16 v[106:109], v[162:165], v[206:209], v[106:109]
	v_mfma_f32_16x16x32_bf16 v[98:101], v[170:173], v[206:209], v[98:101]
	v_mfma_f32_16x16x32_bf16 v[90:93], v[162:165], v[214:217], v[90:93]
	v_mfma_f32_16x16x32_bf16 v[82:85], v[170:173], v[214:217], v[82:85]
	v_mfma_f32_16x16x32_bf16 v[74:77], v[162:165], v[222:225], v[74:77]
	v_mfma_f32_16x16x32_bf16 v[66:69], v[170:173], v[222:225], v[66:69]
	v_mfma_f32_16x16x32_bf16 v[122:125], v[166:169], v[182:185], v[122:125]
	v_mfma_f32_16x16x32_bf16 v[114:117], v[174:177], v[182:185], v[114:117]
	v_mfma_f32_16x16x32_bf16 v[106:109], v[166:169], v[210:213], v[106:109]
	v_mfma_f32_16x16x32_bf16 v[98:101], v[174:177], v[210:213], v[98:101]
	v_mfma_f32_16x16x32_bf16 v[90:93], v[166:169], v[218:221], v[90:93]
	v_mfma_f32_16x16x32_bf16 v[82:85], v[174:177], v[218:221], v[82:85]
	v_mfma_f32_16x16x32_bf16 v[74:77], v[166:169], v[226:229], v[74:77]
	v_mfma_f32_16x16x32_bf16 v[66:69], v[174:177], v[226:229], v[66:69]
	s_setprio 0
	s_barrier
	s_add_i32 s24, 0, 0x1c000
	s_add_i32 s25, s48, s29
	v_add_u32_e32 v205, s24, v143
	v_lshl_add_u64 v[140:141], v[140:141], 0, s[94:95]
	s_mov_b32 m0, s25
	ds_read_b128 v[230:233], v205
	ds_read_b128 v[234:237], v205 offset:1024
	ds_read_b128 v[238:241], v205 offset:2048
	ds_read_b128 v[242:245], v205 offset:3072
	global_load_lds_dwordx4 v[140:141], off
	v_lshl_add_u64 v[140:141], v[186:187], 0, s[94:95]
	s_add_i32 m0, s25, 0x2000
	s_nop 0
	global_load_lds_dwordx4 v[140:141], off
	s_barrier
	s_waitcnt lgkmcnt(0)
	s_setprio 1
	v_mfma_f32_16x16x32_bf16 v[126:129], v[230:233], v[178:181], v[126:129]
	v_mfma_f32_16x16x32_bf16 v[118:121], v[238:241], v[178:181], v[118:121]
	v_mfma_f32_16x16x32_bf16 v[110:113], v[230:233], v[206:209], v[110:113]
	v_mfma_f32_16x16x32_bf16 v[102:105], v[238:241], v[206:209], v[102:105]
	v_mfma_f32_16x16x32_bf16 v[94:97], v[230:233], v[214:217], v[94:97]
	v_mfma_f32_16x16x32_bf16 v[86:89], v[238:241], v[214:217], v[86:89]
	v_mfma_f32_16x16x32_bf16 v[78:81], v[230:233], v[222:225], v[78:81]
	v_mfma_f32_16x16x32_bf16 v[70:73], v[238:241], v[222:225], v[70:73]
	v_mfma_f32_16x16x32_bf16 v[126:129], v[234:237], v[182:185], v[126:129]
	v_mfma_f32_16x16x32_bf16 v[118:121], v[242:245], v[182:185], v[118:121]
	v_mfma_f32_16x16x32_bf16 v[110:113], v[234:237], v[210:213], v[110:113]
	v_mfma_f32_16x16x32_bf16 v[102:105], v[242:245], v[210:213], v[102:105]
	v_mfma_f32_16x16x32_bf16 v[94:97], v[234:237], v[218:221], v[94:97]
	v_mfma_f32_16x16x32_bf16 v[86:89], v[242:245], v[218:221], v[86:89]
	v_mfma_f32_16x16x32_bf16 v[78:81], v[234:237], v[226:229], v[78:81]
	v_mfma_f32_16x16x32_bf16 v[70:73], v[242:245], v[226:229], v[70:73]
	s_setprio 0
	s_mov_b32 m0, s37
	v_lshl_add_u64 v[140:141], v[246:247], 0, s[94:95]
	s_barrier
	ds_read_b128 v[178:181], v145 offset:49152
	ds_read_b128 v[182:185], v145 offset:50176
	ds_read_b128 v[206:209], v145 offset:51200
	ds_read_b128 v[210:213], v145 offset:52224
	ds_read_b128 v[214:217], v145 offset:53248
	ds_read_b128 v[218:221], v145 offset:54272
	ds_read_b128 v[222:225], v145 offset:55296
	ds_read_b128 v[226:229], v145 offset:56320
	global_load_lds_dwordx4 v[140:141], off
	v_lshl_add_u64 v[140:141], v[248:249], 0, s[94:95]
	s_mov_b32 m0, s40
	s_nop 0
	global_load_lds_dwordx4 v[140:141], off
	s_barrier
	s_waitcnt lgkmcnt(0)
	s_setprio 1
	v_mfma_f32_16x16x32_bf16 v[58:61], v[162:165], v[178:181], v[58:61]
	v_mfma_f32_16x16x32_bf16 v[50:53], v[170:173], v[178:181], v[50:53]
	v_mfma_f32_16x16x32_bf16 v[42:45], v[162:165], v[206:209], v[42:45]
	v_mfma_f32_16x16x32_bf16 v[34:37], v[170:173], v[206:209], v[34:37]
	v_mfma_f32_16x16x32_bf16 v[26:29], v[162:165], v[214:217], v[26:29]
	v_mfma_f32_16x16x32_bf16 v[18:21], v[170:173], v[214:217], v[18:21]
	v_mfma_f32_16x16x32_bf16 v[10:13], v[162:165], v[222:225], v[10:13]
	v_mfma_f32_16x16x32_bf16 v[6:9], v[170:173], v[222:225], v[6:9]
	v_mfma_f32_16x16x32_bf16 v[58:61], v[166:169], v[182:185], v[58:61]
	v_mfma_f32_16x16x32_bf16 v[50:53], v[174:177], v[182:185], v[50:53]
	v_mfma_f32_16x16x32_bf16 v[42:45], v[166:169], v[210:213], v[42:45]
	v_mfma_f32_16x16x32_bf16 v[34:37], v[174:177], v[210:213], v[34:37]
	v_mfma_f32_16x16x32_bf16 v[26:29], v[166:169], v[218:221], v[26:29]
	v_mfma_f32_16x16x32_bf16 v[18:21], v[174:177], v[218:221], v[18:21]
	v_mfma_f32_16x16x32_bf16 v[10:13], v[166:169], v[226:229], v[10:13]
	v_mfma_f32_16x16x32_bf16 v[6:9], v[174:177], v[226:229], v[6:9]
	s_setprio 0
	s_barrier
	s_add_u32 s22, s22, 0x40080
	s_addc_u32 s23, s23, 0
	s_add_i32 s24, s24, s29
	v_lshl_add_u64 v[140:141], s[22:23], 0, v[0:1]
	s_mov_b32 m0, s24
	s_nop 0
	global_load_lds_dwordx4 v[140:141], off
	v_lshl_add_u64 v[140:141], s[22:23], 0, v[130:131]
	s_add_i32 m0, s24, 0x2000
	s_nop 0
	global_load_lds_dwordx4 v[140:141], off
	s_waitcnt vmcnt(6)
	s_barrier
	s_setprio 1
	v_mfma_f32_16x16x32_bf16 v[62:65], v[230:233], v[178:181], v[62:65]
	v_mfma_f32_16x16x32_bf16 v[54:57], v[238:241], v[178:181], v[54:57]
	v_mfma_f32_16x16x32_bf16 v[46:49], v[230:233], v[206:209], v[46:49]
	v_mfma_f32_16x16x32_bf16 v[38:41], v[238:241], v[206:209], v[38:41]
	v_mfma_f32_16x16x32_bf16 v[30:33], v[230:233], v[214:217], v[30:33]
	v_mfma_f32_16x16x32_bf16 v[22:25], v[238:241], v[214:217], v[22:25]
	v_mfma_f32_16x16x32_bf16 v[14:17], v[230:233], v[222:225], v[14:17]
	v_mfma_f32_16x16x32_bf16 v[2:5], v[238:241], v[222:225], v[2:5]
	v_mfma_f32_16x16x32_bf16 v[62:65], v[234:237], v[182:185], v[62:65]
	v_mfma_f32_16x16x32_bf16 v[54:57], v[242:245], v[182:185], v[54:57]
	v_mfma_f32_16x16x32_bf16 v[46:49], v[234:237], v[210:213], v[46:49]
	v_mfma_f32_16x16x32_bf16 v[38:41], v[242:245], v[210:213], v[38:41]
	v_mfma_f32_16x16x32_bf16 v[30:33], v[234:237], v[218:221], v[30:33]
	v_mfma_f32_16x16x32_bf16 v[22:25], v[242:245], v[218:221], v[22:25]
	v_mfma_f32_16x16x32_bf16 v[14:17], v[234:237], v[226:229], v[14:17]
	v_mfma_f32_16x16x32_bf16 v[2:5], v[242:245], v[226:229], v[2:5]
	s_setprio 0
	s_add_i32 s47, s47, 2
	s_add_u32 s20, s20, 0x100
	s_addc_u32 s21, s21, 0
	s_add_u32 s45, s45, 0x100
	s_addc_u32 s46, s46, 0
	s_cmp_gt_u32 s47, 13
	s_barrier
	s_cbranch_scc0 .LBB0_586
	v_pk_mul_f32 v[164:165], v[122:123], s[4:5] op_sel_hi:[1,0]
	v_pk_mul_f32 v[122:123], v[122:123], v[126:127]
	v_pk_mul_f32 v[126:127], v[114:115], s[4:5] op_sel_hi:[1,0]
	v_pk_mul_f32 v[114:115], v[114:115], v[118:119]
	v_exp_f32_e32 v126, v126
	v_exp_f32_e32 v127, v127
	v_pk_mul_f32 v[128:129], v[124:125], v[128:129]
	v_pk_mul_f32 v[124:125], v[124:125], s[4:5] op_sel_hi:[1,0]
	v_exp_f32_e32 v164, v164
	v_pk_add_f32 v[126:127], v[126:127], 1.0 op_sel_hi:[1,0]
	v_exp_f32_e32 v165, v165
	v_rcp_f32_e32 v126, v126
	v_rcp_f32_e32 v127, v127
	v_exp_f32_e32 v124, v124
	v_exp_f32_e32 v125, v125
	v_pk_add_f32 v[164:165], v[164:165], 1.0 op_sel_hi:[1,0]
	v_pk_mul_f32 v[118:119], v[126:127], v[114:115]
	v_pk_mul_f32 v[114:115], v[116:117], s[4:5] op_sel_hi:[1,0]
	v_pk_add_f32 v[124:125], v[124:125], 1.0 op_sel_hi:[1,0]
	v_exp_f32_e32 v114, v114
	v_exp_f32_e32 v115, v115
	v_rcp_f32_e32 v164, v164
	v_rcp_f32_e32 v165, v165
	v_rcp_f32_e32 v124, v124
	v_pk_add_f32 v[114:115], v[114:115], 1.0 op_sel_hi:[1,0]
	v_rcp_f32_e32 v125, v125
	v_rcp_f32_e32 v114, v114
	v_rcp_f32_e32 v115, v115
	v_lshl_or_b32 v140, s42, 7, v144
	v_ashrrev_i32_e32 v141, 31, v140
	v_lshl_add_u32 v162, s2, 8, v142
	v_lshl_add_u64 v[140:141], v[140:141], 1, s[14:15]
	v_pk_mul_f32 v[120:121], v[116:117], v[120:121]
	v_pk_mul_f32 v[122:123], v[164:165], v[122:123]
	v_pk_mul_f32 v[124:125], v[124:125], v[128:129]
	v_pk_mul_f32 v[120:121], v[114:115], v[120:121]
	v_mad_i64_i32 v[126:127], s[20:21], v162, s91, v[140:141]
	v_cvt_pk_bf16_f32 v114, v122, v123
	v_cvt_pk_bf16_f32 v115, v124, v125
	v_cvt_pk_bf16_f32 v116, v118, v119
	v_cvt_pk_bf16_f32 v117, v120, v121
	global_store_dwordx4 v[126:127], v[114:117], off
	v_pk_mul_f32 v[112:113], v[108:109], v[112:113]
	v_pk_mul_f32 v[108:109], v[108:109], s[4:5] op_sel_hi:[1,0]
	v_pk_mul_f32 v[114:115], v[106:107], s[4:5] op_sel_hi:[1,0]
	v_pk_mul_f32 v[106:107], v[106:107], v[110:111]
	v_pk_mul_f32 v[110:111], v[98:99], s[4:5] op_sel_hi:[1,0]
	v_pk_mul_f32 v[98:99], v[98:99], v[102:103]
	v_exp_f32_e32 v110, v110
	v_exp_f32_e32 v111, v111
	v_exp_f32_e32 v114, v114
	v_exp_f32_e32 v115, v115
	v_exp_f32_e32 v108, v108
	v_pk_add_f32 v[110:111], v[110:111], 1.0 op_sel_hi:[1,0]
	v_exp_f32_e32 v109, v109
	v_rcp_f32_e32 v110, v110
	v_rcp_f32_e32 v111, v111
	v_pk_add_f32 v[114:115], v[114:115], 1.0 op_sel_hi:[1,0]
	v_pk_add_f32 v[108:109], v[108:109], 1.0 op_sel_hi:[1,0]
	v_rcp_f32_e32 v114, v114
	v_pk_mul_f32 v[102:103], v[110:111], v[98:99]
	v_pk_mul_f32 v[98:99], v[100:101], s[4:5] op_sel_hi:[1,0]
	v_rcp_f32_e32 v115, v115
	v_exp_f32_e32 v98, v98
	v_exp_f32_e32 v99, v99
	v_rcp_f32_e32 v108, v108
	v_rcp_f32_e32 v109, v109
	v_or_b32_e32 v116, 16, v162
	v_pk_add_f32 v[98:99], v[98:99], 1.0 op_sel_hi:[1,0]
	v_pk_mul_f32 v[104:105], v[100:101], v[104:105]
	v_rcp_f32_e32 v98, v98
	v_rcp_f32_e32 v99, v99
	v_pk_mul_f32 v[106:107], v[114:115], v[106:107]
	v_pk_mul_f32 v[108:109], v[108:109], v[112:113]
	v_mad_i64_i32 v[110:111], s[20:21], v116, s91, v[140:141]
	v_pk_mul_f32 v[104:105], v[98:99], v[104:105]
	v_cvt_pk_bf16_f32 v98, v106, v107
	v_cvt_pk_bf16_f32 v99, v108, v109
	v_cvt_pk_bf16_f32 v100, v102, v103
	v_pk_mul_f32 v[96:97], v[92:93], v[96:97]
	v_cvt_pk_bf16_f32 v101, v104, v105
	global_store_dwordx4 v[110:111], v[98:101], off
	v_pk_mul_f32 v[92:93], v[92:93], s[4:5] op_sel_hi:[1,0]
	v_pk_mul_f32 v[88:89], v[84:85], v[88:89]
	v_pk_mul_f32 v[98:99], v[90:91], s[4:5] op_sel_hi:[1,0]
	v_pk_mul_f32 v[90:91], v[90:91], v[94:95]
	v_pk_mul_f32 v[94:95], v[82:83], s[4:5] op_sel_hi:[1,0]
	v_pk_mul_f32 v[82:83], v[82:83], v[86:87]
	v_exp_f32_e32 v94, v94
	v_exp_f32_e32 v95, v95
	v_exp_f32_e32 v98, v98
	v_exp_f32_e32 v99, v99
	v_exp_f32_e32 v92, v92
	v_pk_add_f32 v[94:95], v[94:95], 1.0 op_sel_hi:[1,0]
	v_exp_f32_e32 v93, v93
	v_rcp_f32_e32 v94, v94
	v_rcp_f32_e32 v95, v95
	v_pk_add_f32 v[98:99], v[98:99], 1.0 op_sel_hi:[1,0]
	v_pk_add_f32 v[92:93], v[92:93], 1.0 op_sel_hi:[1,0]
	v_rcp_f32_e32 v98, v98
	v_pk_mul_f32 v[86:87], v[94:95], v[82:83]
	v_pk_mul_f32 v[82:83], v[84:85], s[4:5] op_sel_hi:[1,0]
	v_rcp_f32_e32 v99, v99
	v_exp_f32_e32 v82, v82
	v_exp_f32_e32 v83, v83
	v_rcp_f32_e32 v92, v92
	v_rcp_f32_e32 v93, v93
	v_or_b32_e32 v100, 32, v162
	v_pk_add_f32 v[82:83], v[82:83], 1.0 op_sel_hi:[1,0]
	v_pk_mul_f32 v[90:91], v[98:99], v[90:91]
	v_rcp_f32_e32 v82, v82
	v_rcp_f32_e32 v83, v83
	v_pk_mul_f32 v[92:93], v[92:93], v[96:97]
	v_mad_i64_i32 v[94:95], s[20:21], v100, s91, v[140:141]
	v_pk_mul_f32 v[88:89], v[82:83], v[88:89]
	v_cvt_pk_bf16_f32 v82, v90, v91
	v_cvt_pk_bf16_f32 v83, v92, v93
	v_cvt_pk_bf16_f32 v84, v86, v87
	v_pk_mul_f32 v[80:81], v[76:77], v[80:81]
	v_cvt_pk_bf16_f32 v85, v88, v89
	global_store_dwordx4 v[94:95], v[82:85], off
	v_pk_mul_f32 v[76:77], v[76:77], s[4:5] op_sel_hi:[1,0]
	v_pk_mul_f32 v[72:73], v[68:69], v[72:73]
	v_pk_mul_f32 v[82:83], v[74:75], s[4:5] op_sel_hi:[1,0]
	v_pk_mul_f32 v[74:75], v[74:75], v[78:79]
	v_pk_mul_f32 v[78:79], v[66:67], s[4:5] op_sel_hi:[1,0]
	v_pk_mul_f32 v[66:67], v[66:67], v[70:71]
	v_exp_f32_e32 v78, v78
	v_exp_f32_e32 v79, v79
	v_exp_f32_e32 v82, v82
	v_exp_f32_e32 v83, v83
	v_exp_f32_e32 v76, v76
	v_pk_add_f32 v[78:79], v[78:79], 1.0 op_sel_hi:[1,0]
	v_exp_f32_e32 v77, v77
	v_rcp_f32_e32 v78, v78
	v_rcp_f32_e32 v79, v79
	v_pk_add_f32 v[82:83], v[82:83], 1.0 op_sel_hi:[1,0]
	v_pk_add_f32 v[76:77], v[76:77], 1.0 op_sel_hi:[1,0]
	v_rcp_f32_e32 v82, v82
	v_pk_mul_f32 v[70:71], v[78:79], v[66:67]
	v_pk_mul_f32 v[66:67], v[68:69], s[4:5] op_sel_hi:[1,0]
	v_rcp_f32_e32 v83, v83
	v_exp_f32_e32 v66, v66
	v_exp_f32_e32 v67, v67
	v_rcp_f32_e32 v76, v76
	v_rcp_f32_e32 v77, v77
	v_or_b32_e32 v84, 48, v162
	v_pk_add_f32 v[66:67], v[66:67], 1.0 op_sel_hi:[1,0]
	v_pk_mul_f32 v[74:75], v[82:83], v[74:75]
	v_rcp_f32_e32 v66, v66
	v_rcp_f32_e32 v67, v67
	v_pk_mul_f32 v[76:77], v[76:77], v[80:81]
	v_mad_i64_i32 v[78:79], s[20:21], v84, s91, v[140:141]
	v_pk_mul_f32 v[72:73], v[66:67], v[72:73]
	v_cvt_pk_bf16_f32 v66, v74, v75
	v_cvt_pk_bf16_f32 v67, v76, v77
	v_cvt_pk_bf16_f32 v68, v70, v71
	v_pk_mul_f32 v[64:65], v[60:61], v[64:65]
	v_cvt_pk_bf16_f32 v69, v72, v73
	global_store_dwordx4 v[78:79], v[66:69], off
	v_pk_mul_f32 v[60:61], v[60:61], s[4:5] op_sel_hi:[1,0]
	v_pk_mul_f32 v[56:57], v[52:53], v[56:57]
	v_pk_mul_f32 v[66:67], v[58:59], s[4:5] op_sel_hi:[1,0]
	v_pk_mul_f32 v[58:59], v[58:59], v[62:63]
	v_pk_mul_f32 v[62:63], v[50:51], s[4:5] op_sel_hi:[1,0]
	v_pk_mul_f32 v[50:51], v[50:51], v[54:55]
	v_exp_f32_e32 v62, v62
	v_exp_f32_e32 v63, v63
	v_exp_f32_e32 v66, v66
	v_exp_f32_e32 v67, v67
	v_exp_f32_e32 v60, v60
	v_pk_add_f32 v[62:63], v[62:63], 1.0 op_sel_hi:[1,0]
	v_exp_f32_e32 v61, v61
	v_rcp_f32_e32 v62, v62
	v_rcp_f32_e32 v63, v63
	v_pk_add_f32 v[66:67], v[66:67], 1.0 op_sel_hi:[1,0]
	v_pk_add_f32 v[60:61], v[60:61], 1.0 op_sel_hi:[1,0]
	v_rcp_f32_e32 v66, v66
	v_pk_mul_f32 v[54:55], v[62:63], v[50:51]
	v_pk_mul_f32 v[50:51], v[52:53], s[4:5] op_sel_hi:[1,0]
	v_rcp_f32_e32 v67, v67
	v_exp_f32_e32 v50, v50
	v_exp_f32_e32 v51, v51
	v_rcp_f32_e32 v60, v60
	v_rcp_f32_e32 v61, v61
	v_add_u32_e32 v68, 0x80, v162
	v_pk_add_f32 v[50:51], v[50:51], 1.0 op_sel_hi:[1,0]
	v_pk_mul_f32 v[58:59], v[66:67], v[58:59]
	v_rcp_f32_e32 v50, v50
	v_rcp_f32_e32 v51, v51
	v_pk_mul_f32 v[60:61], v[60:61], v[64:65]
	v_mad_i64_i32 v[62:63], s[20:21], v68, s91, v[140:141]
	v_pk_mul_f32 v[56:57], v[50:51], v[56:57]
	v_cvt_pk_bf16_f32 v50, v58, v59
	v_cvt_pk_bf16_f32 v51, v60, v61
	v_cvt_pk_bf16_f32 v52, v54, v55
	v_pk_mul_f32 v[48:49], v[44:45], v[48:49]
	v_cvt_pk_bf16_f32 v53, v56, v57
	global_store_dwordx4 v[62:63], v[50:53], off
	v_pk_mul_f32 v[44:45], v[44:45], s[4:5] op_sel_hi:[1,0]
	v_pk_mul_f32 v[40:41], v[36:37], v[40:41]
	v_pk_mul_f32 v[50:51], v[42:43], s[4:5] op_sel_hi:[1,0]
	v_pk_mul_f32 v[42:43], v[42:43], v[46:47]
	v_pk_mul_f32 v[46:47], v[34:35], s[4:5] op_sel_hi:[1,0]
	v_pk_mul_f32 v[34:35], v[34:35], v[38:39]
	v_exp_f32_e32 v46, v46
	v_exp_f32_e32 v47, v47
	v_exp_f32_e32 v50, v50
	v_exp_f32_e32 v51, v51
	v_exp_f32_e32 v44, v44
	v_pk_add_f32 v[46:47], v[46:47], 1.0 op_sel_hi:[1,0]
	v_exp_f32_e32 v45, v45
	v_rcp_f32_e32 v46, v46
	v_rcp_f32_e32 v47, v47
	v_pk_add_f32 v[50:51], v[50:51], 1.0 op_sel_hi:[1,0]
	v_pk_add_f32 v[44:45], v[44:45], 1.0 op_sel_hi:[1,0]
	v_rcp_f32_e32 v50, v50
	v_pk_mul_f32 v[38:39], v[46:47], v[34:35]
	v_pk_mul_f32 v[34:35], v[36:37], s[4:5] op_sel_hi:[1,0]
	v_rcp_f32_e32 v51, v51
	v_exp_f32_e32 v34, v34
	v_exp_f32_e32 v35, v35
	v_rcp_f32_e32 v44, v44
	v_rcp_f32_e32 v45, v45
	v_add_u32_e32 v52, 0x90, v162
	v_pk_add_f32 v[34:35], v[34:35], 1.0 op_sel_hi:[1,0]
	v_pk_mul_f32 v[42:43], v[50:51], v[42:43]
	v_rcp_f32_e32 v34, v34
	v_rcp_f32_e32 v35, v35
	v_pk_mul_f32 v[44:45], v[44:45], v[48:49]
	v_mad_i64_i32 v[46:47], s[20:21], v52, s91, v[140:141]
	v_pk_mul_f32 v[40:41], v[34:35], v[40:41]
	v_cvt_pk_bf16_f32 v34, v42, v43
	v_cvt_pk_bf16_f32 v35, v44, v45
	v_cvt_pk_bf16_f32 v36, v38, v39
	v_pk_mul_f32 v[32:33], v[28:29], v[32:33]
	v_cvt_pk_bf16_f32 v37, v40, v41
	global_store_dwordx4 v[46:47], v[34:37], off
	v_pk_mul_f32 v[28:29], v[28:29], s[4:5] op_sel_hi:[1,0]
	v_pk_mul_f32 v[24:25], v[20:21], v[24:25]
	v_pk_mul_f32 v[34:35], v[26:27], s[4:5] op_sel_hi:[1,0]
	v_pk_mul_f32 v[26:27], v[26:27], v[30:31]
	v_pk_mul_f32 v[30:31], v[18:19], s[4:5] op_sel_hi:[1,0]
	v_pk_mul_f32 v[18:19], v[18:19], v[22:23]
	v_exp_f32_e32 v30, v30
	v_exp_f32_e32 v31, v31
	v_exp_f32_e32 v34, v34
	v_exp_f32_e32 v35, v35
	v_exp_f32_e32 v28, v28
	v_pk_add_f32 v[30:31], v[30:31], 1.0 op_sel_hi:[1,0]
	v_exp_f32_e32 v29, v29
	v_rcp_f32_e32 v30, v30
	v_rcp_f32_e32 v31, v31
	v_pk_add_f32 v[34:35], v[34:35], 1.0 op_sel_hi:[1,0]
	v_pk_add_f32 v[28:29], v[28:29], 1.0 op_sel_hi:[1,0]
	v_rcp_f32_e32 v34, v34
	v_pk_mul_f32 v[22:23], v[30:31], v[18:19]
	v_pk_mul_f32 v[18:19], v[20:21], s[4:5] op_sel_hi:[1,0]
	v_rcp_f32_e32 v35, v35
	v_exp_f32_e32 v18, v18
	v_exp_f32_e32 v19, v19
	v_rcp_f32_e32 v28, v28
	v_rcp_f32_e32 v29, v29
	v_add_u32_e32 v36, 0xa0, v162
	v_pk_add_f32 v[18:19], v[18:19], 1.0 op_sel_hi:[1,0]
	v_pk_mul_f32 v[26:27], v[34:35], v[26:27]
	v_rcp_f32_e32 v18, v18
	v_rcp_f32_e32 v19, v19
	v_pk_mul_f32 v[28:29], v[28:29], v[32:33]
	v_mad_i64_i32 v[30:31], s[20:21], v36, s91, v[140:141]
	v_pk_mul_f32 v[24:25], v[18:19], v[24:25]
	v_cvt_pk_bf16_f32 v18, v26, v27
	v_cvt_pk_bf16_f32 v19, v28, v29
	v_cvt_pk_bf16_f32 v20, v22, v23
	v_pk_mul_f32 v[2:3], v[6:7], v[2:3]
	v_cvt_pk_bf16_f32 v21, v24, v25
	global_store_dwordx4 v[30:31], v[18:21], off
	v_pk_mul_f32 v[16:17], v[12:13], v[16:17]
	v_pk_mul_f32 v[12:13], v[12:13], s[4:5] op_sel_hi:[1,0]
	v_pk_mul_f32 v[18:19], v[10:11], s[4:5] op_sel_hi:[1,0]
	v_pk_mul_f32 v[10:11], v[10:11], v[14:15]
	v_pk_mul_f32 v[14:15], v[6:7], s[4:5] op_sel_hi:[1,0]
	v_exp_f32_e32 v18, v18
	v_exp_f32_e32 v14, v14
	v_exp_f32_e32 v15, v15
	v_exp_f32_e32 v19, v19
	v_exp_f32_e32 v12, v12
	v_exp_f32_e32 v13, v13
	v_pk_add_f32 v[14:15], v[14:15], 1.0 op_sel_hi:[1,0]
	v_pk_add_f32 v[18:19], v[18:19], 1.0 op_sel_hi:[1,0]
	v_rcp_f32_e32 v14, v14
	v_rcp_f32_e32 v15, v15
	v_pk_add_f32 v[12:13], v[12:13], 1.0 op_sel_hi:[1,0]
	v_rcp_f32_e32 v18, v18
	v_rcp_f32_e32 v19, v19
	v_pk_mul_f32 v[6:7], v[14:15], v[2:3]
	v_pk_mul_f32 v[2:3], v[8:9], s[4:5] op_sel_hi:[1,0]
	v_rcp_f32_e32 v12, v12
	v_exp_f32_e32 v2, v2
	v_exp_f32_e32 v3, v3
	v_rcp_f32_e32 v13, v13
	v_add_u32_e32 v20, 0xb0, v162
	v_mad_i64_i32 v[14:15], s[20:21], v20, s91, v[140:141]
	v_pk_add_f32 v[2:3], v[2:3], 1.0 op_sel_hi:[1,0]
	v_pk_mul_f32 v[4:5], v[8:9], v[4:5]
	v_rcp_f32_e32 v2, v2
	v_rcp_f32_e32 v3, v3
	s_and_b64 vcc, exec, s[38:39]
	s_mov_b32 s42, s0
	s_mov_b32 s2, s8
	s_mov_b64 s[22:23], s[18:19]
	s_mov_b64 s[20:21], s[16:17]
	v_pk_mul_f32 v[10:11], v[18:19], v[10:11]
	v_pk_mul_f32 v[12:13], v[12:13], v[16:17]
	v_pk_mul_f32 v[8:9], v[2:3], v[4:5]
	v_cvt_pk_bf16_f32 v2, v10, v11
	v_cvt_pk_bf16_f32 v3, v12, v13
	v_cvt_pk_bf16_f32 v4, v6, v7
	s_nop 0
	v_cvt_pk_bf16_f32 v5, v8, v9
	global_store_dwordx4 v[14:15], v[2:5], off
	s_cbranch_vccz .LBB0_579
	s_waitcnt vmcnt(0)
	s_cmpk_gt_u32 s26, 0xff
	s_cbranch_scc1 .LBB0_590
	s_barrier
